# idx score loop: 8 key-fragment LDS reads up front with counted lgkmcnt; EpiUp stats loads at tile start
# baseline (speedup 1.0000x reference)
; #define LAS __attribute__((address_space(3)))
; __device__ __forceinline__ float relu1(float a) { return __builtin_amdgcn_fmed3f(a, 0.f, 3.0e38f); }
; __device__ __forceinline__ void idx_phase(const int TID, const int BID, PP p, LAS unsigned char* lds) {
;     ...
;                 bf16x8 Bf0[4], Bf1[4];
; #pragma unroll
;                 for (int ks = 0; ks < 4; ++ks) { Bf0[ks] = *(const LAS bf16x8*)(lds + (kt * 32 + rr) * 144 + g2 * 64 + ks * 16); Bf1[ks] = *(const LAS bf16x8*)(lds + ((kt + 1) * 32 + rr) * 144 + g2 * 64 + ks * 16); }
; #pragma unroll
;                 for (int ks = 0; ks < 4; ++ks) { acc0 = __builtin_amdgcn_mfma_f32_32x32x16_bf16(A[ks], Bf0[ks], acc0, 0, 0, 0); acc1 = __builtin_amdgcn_mfma_f32_32x32x16_bf16(A[ks], Bf1[ks], acc1, 0, 0, 0); }
;                 float s0 = 0.f, s1 = 0.f, t0 = 0.f, t1 = 0.f;
; #pragma unroll
;                 for (int i = 0; i < 8; ++i) { s0 += relu1(acc0[i]) * wq[i]; s1 += relu1(acc0[8 + i]) * wq[8 + i]; t0 += relu1(acc1[i]) * wq[i]; t1 += relu1(acc1[8 + i]) * wq[8 + i]; }
;                 s0 += __shfl_xor(s0, 32); s1 += __shfl_xor(s1, 32); t0 += __shfl_xor(t0, 32); t1 += __shfl_xor(t1, 32);
;                 _Float16* so = Sc + (size_t)(tokq + g2) * SEQ + key0 + kt * 32 + rr;
;                 so[0] = (_Float16)(g2 ? s1 : s0); so[32] = (_Float16)(g2 ? t1 : t0);
.LBB0_736:
	ds_read_b128 v[0:3], v200
	ds_read_b128 v[16:19], v200 offset:4608
	ds_read_b128 v[208:211], v200 offset:16
	ds_read_b128 v[212:215], v200 offset:4624
	ds_read_b128 v[216:219], v200 offset:32
	ds_read_b128 v[220:223], v200 offset:4640
	ds_read_b128 v[224:227], v200 offset:48
	ds_read_b128 v[228:231], v200 offset:4656
	v_add_u32_e32 v200, 0x2400, v200
	s_add_i32 s12, s12, 2
	s_cmp_lt_i32 s12, s1
	s_waitcnt lgkmcnt(7)
	v_mfma_f32_32x32x16_bf16 v[0:15], v[128:131], v[0:3], 0
	s_waitcnt lgkmcnt(6)
	v_mfma_f32_32x32x16_bf16 v[16:31], v[128:131], v[16:19], 0
	s_waitcnt lgkmcnt(5)
	v_mfma_f32_32x32x16_bf16 v[0:15], v[132:135], v[208:211], v[0:15]
	s_waitcnt lgkmcnt(4)
	v_mfma_f32_32x32x16_bf16 v[16:31], v[132:135], v[212:215], v[16:31]
	s_waitcnt lgkmcnt(3)
	v_mfma_f32_32x32x16_bf16 v[0:15], v[136:139], v[216:219], v[0:15]
	s_waitcnt lgkmcnt(2)
	v_mfma_f32_32x32x16_bf16 v[16:31], v[136:139], v[220:223], v[16:31]
	s_waitcnt lgkmcnt(1)
	v_mfma_f32_32x32x16_bf16 v[0:15], v[140:143], v[224:227], v[0:15]
	s_waitcnt lgkmcnt(0)
	v_mfma_f32_32x32x16_bf16 v[16:31], v[140:143], v[228:231], v[16:31]
	s_nop 9
	v_med3_f32 v0, v0, 0, v192
	v_med3_f32 v8, v8, 0, v192
	v_med3_f32 v1, v1, 0, v192
	v_med3_f32 v9, v9, 0, v192
	v_fma_f32 v0, v144, v0, 0
	v_fma_f32 v8, v152, v8, 0
	v_med3_f32 v2, v2, 0, v192
	v_med3_f32 v16, v16, 0, v192
	v_med3_f32 v24, v24, 0, v192
	v_med3_f32 v17, v17, 0, v192
	v_med3_f32 v25, v25, 0, v192
	v_med3_f32 v10, v10, 0, v192
	v_fma_f32 v16, v144, v16, 0
	v_fma_f32 v24, v152, v24, 0
	v_fmac_f32_e32 v0, v145, v1
	v_fmac_f32_e32 v8, v153, v9
	v_med3_f32 v18, v18, 0, v192
	v_med3_f32 v26, v26, 0, v192
	v_med3_f32 v3, v3, 0, v192
	v_med3_f32 v11, v11, 0, v192
	v_fmac_f32_e32 v16, v145, v17
	v_fmac_f32_e32 v24, v153, v25
	v_fmac_f32_e32 v0, v146, v2
	v_fmac_f32_e32 v8, v154, v10
	v_med3_f32 v19, v19, 0, v192
	v_med3_f32 v27, v27, 0, v192
	v_med3_f32 v4, v4, 0, v192
	v_med3_f32 v12, v12, 0, v192
	v_fmac_f32_e32 v16, v146, v18
	v_fmac_f32_e32 v24, v154, v26
	v_fmac_f32_e32 v0, v147, v3
	v_fmac_f32_e32 v8, v155, v11
	v_med3_f32 v20, v20, 0, v192
	v_med3_f32 v28, v28, 0, v192
	v_med3_f32 v5, v5, 0, v192
	v_med3_f32 v13, v13, 0, v192
	v_fmac_f32_e32 v16, v147, v19
	v_fmac_f32_e32 v24, v155, v27
	v_fmac_f32_e32 v0, v148, v4
	v_fmac_f32_e32 v8, v156, v12
	v_med3_f32 v21, v21, 0, v192
	v_med3_f32 v29, v29, 0, v192
	v_med3_f32 v6, v6, 0, v192
	v_med3_f32 v14, v14, 0, v192
	v_fmac_f32_e32 v16, v148, v20
	v_fmac_f32_e32 v24, v156, v28
	v_fmac_f32_e32 v0, v149, v5
	v_fmac_f32_e32 v8, v157, v13
	v_med3_f32 v22, v22, 0, v192
	v_med3_f32 v30, v30, 0, v192
	v_med3_f32 v7, v7, 0, v192
	v_med3_f32 v15, v15, 0, v192
	v_fmac_f32_e32 v16, v149, v21
	v_fmac_f32_e32 v24, v157, v29
	v_fmac_f32_e32 v0, v150, v6
	v_fmac_f32_e32 v8, v158, v14
	v_med3_f32 v23, v23, 0, v192
	v_med3_f32 v31, v31, 0, v192
	v_fmac_f32_e32 v16, v150, v22
	v_fmac_f32_e32 v24, v158, v30
	v_fmac_f32_e32 v0, v151, v7
	v_fmac_f32_e32 v8, v159, v15
	v_fmac_f32_e32 v16, v151, v23
	v_fmac_f32_e32 v24, v159, v31
	ds_bpermute_b32 v1, v196, v0
	ds_bpermute_b32 v2, v196, v8
	ds_bpermute_b32 v3, v196, v16
	ds_bpermute_b32 v4, v196, v24
	s_waitcnt lgkmcnt(3)
	v_add_f32_e32 v0, v0, v1
	s_waitcnt lgkmcnt(2)
	v_add_f32_e32 v1, v8, v2
	s_waitcnt lgkmcnt(1)
	v_add_f32_e32 v2, v16, v3
	s_waitcnt lgkmcnt(0)
	v_add_f32_e32 v3, v24, v4
	v_cndmask_b32_e32 v0, v1, v0, vcc
	v_cndmask_b32_e32 v1, v3, v2, vcc
	v_cvt_f16_f32_e32 v0, v0
	v_cvt_f16_f32_e32 v1, v1
	global_store_short v[176:177], v0, off
	global_store_short v[176:177], v1, off offset:64
	v_lshl_add_u64 v[176:177], v[176:177], 0, s[90:91]
	s_cbranch_scc1 .LBB0_736
	v_add_u32_e32 v0, s4, v199
	v_ashrrev_i32_e32 v1, 31, v0
	v_lshlrev_b64 v[0:1], 13, v[0:1]
	v_lshl_add_u64 v[128:129], v[174:175], 0, v[0:1]
	s_mov_b32 s8, 0
	v_mov_b32_e32 v130, v181
.LBB0_738:
	ds_read_b128 v[0:3], v130
	ds_read_b128 v[16:19], v130 offset:4608
	ds_read_b128 v[132:135], v130 offset:16
	ds_read_b128 v[212:215], v130 offset:4624
	ds_read_b128 v[216:219], v130 offset:32
	ds_read_b128 v[220:223], v130 offset:4640
	ds_read_b128 v[224:227], v130 offset:48
	ds_read_b128 v[228:231], v130 offset:4656
	v_add_u32_e32 v130, 0x2400, v130
	s_add_i32 s8, s8, 2
	s_cmp_lt_i32 s8, s1
	s_waitcnt lgkmcnt(7)
	v_mfma_f32_32x32x16_bf16 v[0:15], v[96:99], v[0:3], 0
	s_waitcnt lgkmcnt(6)
	v_mfma_f32_32x32x16_bf16 v[16:31], v[96:99], v[16:19], 0
	s_waitcnt lgkmcnt(5)
	v_mfma_f32_32x32x16_bf16 v[0:15], v[100:103], v[132:135], v[0:15]
	s_waitcnt lgkmcnt(4)
	v_mfma_f32_32x32x16_bf16 v[16:31], v[100:103], v[212:215], v[16:31]
	s_waitcnt lgkmcnt(3)
	v_mfma_f32_32x32x16_bf16 v[0:15], v[104:107], v[216:219], v[0:15]
	s_waitcnt lgkmcnt(2)
	v_mfma_f32_32x32x16_bf16 v[16:31], v[104:107], v[220:223], v[16:31]
	s_waitcnt lgkmcnt(1)
	v_mfma_f32_32x32x16_bf16 v[0:15], v[108:111], v[224:227], v[0:15]
	s_waitcnt lgkmcnt(0)
; #define LAS __attribute__((address_space(3)))
; __device__ __forceinline__ float relu1(float a) { return __builtin_amdgcn_fmed3f(a, 0.f, 3.0e38f); }
; __device__ __forceinline__ void idx_phase(const int TID, const int BID, PP p, LAS unsigned char* lds) {
;     ...
;                 bf16x8 Bf0[4], Bf1[4];
; #pragma unroll
;                 for (int ks = 0; ks < 4; ++ks) { Bf0[ks] = *(const LAS bf16x8*)(lds + (kt * 32 + rr) * 144 + g2 * 64 + ks * 16); Bf1[ks] = *(const LAS bf16x8*)(lds + ((kt + 1) * 32 + rr) * 144 + g2 * 64 + ks * 16); }
; #pragma unroll
;                 for (int ks = 0; ks < 4; ++ks) { acc0 = __builtin_amdgcn_mfma_f32_32x32x16_bf16(A[ks], Bf0[ks], acc0, 0, 0, 0); acc1 = __builtin_amdgcn_mfma_f32_32x32x16_bf16(A[ks], Bf1[ks], acc1, 0, 0, 0); }
;                 float s0 = 0.f, s1 = 0.f, t0 = 0.f, t1 = 0.f;
; #pragma unroll
;                 for (int i = 0; i < 8; ++i) { s0 += relu1(acc0[i]) * wq[i]; s1 += relu1(acc0[8 + i]) * wq[8 + i]; t0 += relu1(acc1[i]) * wq[i]; t1 += relu1(acc1[8 + i]) * wq[8 + i]; }
;                 s0 += __shfl_xor(s0, 32); s1 += __shfl_xor(s1, 32); t0 += __shfl_xor(t0, 32); t1 += __shfl_xor(t1, 32);
;                 _Float16* so = Sc + (size_t)(tokq + g2) * SEQ + key0 + kt * 32 + rr;
;                 so[0] = (_Float16)(g2 ? s1 : s0); so[32] = (_Float16)(g2 ? t1 : t0);
	v_mfma_f32_32x32x16_bf16 v[16:31], v[108:111], v[228:231], v[16:31]
	s_nop 9
	v_med3_f32 v0, v0, 0, v192
	v_med3_f32 v8, v8, 0, v192
	v_med3_f32 v1, v1, 0, v192
	v_med3_f32 v9, v9, 0, v192
	v_fma_f32 v0, v112, v0, 0
	v_fma_f32 v8, v120, v8, 0
	v_med3_f32 v2, v2, 0, v192
	v_med3_f32 v16, v16, 0, v192
	v_med3_f32 v24, v24, 0, v192
	v_med3_f32 v17, v17, 0, v192
	v_med3_f32 v25, v25, 0, v192
	v_med3_f32 v10, v10, 0, v192
	v_fma_f32 v16, v112, v16, 0
	v_fma_f32 v24, v120, v24, 0
	v_fmac_f32_e32 v0, v113, v1
	v_fmac_f32_e32 v8, v121, v9
	v_med3_f32 v18, v18, 0, v192
	v_med3_f32 v26, v26, 0, v192
	v_med3_f32 v3, v3, 0, v192
	v_med3_f32 v11, v11, 0, v192
	v_fmac_f32_e32 v16, v113, v17
	v_fmac_f32_e32 v24, v121, v25
	v_fmac_f32_e32 v0, v114, v2
	v_fmac_f32_e32 v8, v122, v10
	v_med3_f32 v19, v19, 0, v192
	v_med3_f32 v27, v27, 0, v192
	v_med3_f32 v4, v4, 0, v192
	v_med3_f32 v12, v12, 0, v192
	v_fmac_f32_e32 v16, v114, v18
	v_fmac_f32_e32 v24, v122, v26
	v_fmac_f32_e32 v0, v115, v3
	v_fmac_f32_e32 v8, v123, v11
	v_med3_f32 v20, v20, 0, v192
	v_med3_f32 v28, v28, 0, v192
	v_med3_f32 v5, v5, 0, v192
	v_med3_f32 v13, v13, 0, v192
	v_fmac_f32_e32 v16, v115, v19
	v_fmac_f32_e32 v24, v123, v27
	v_fmac_f32_e32 v0, v116, v4
	v_fmac_f32_e32 v8, v124, v12
	v_med3_f32 v21, v21, 0, v192
	v_med3_f32 v29, v29, 0, v192
	v_med3_f32 v6, v6, 0, v192
	v_med3_f32 v14, v14, 0, v192
	v_fmac_f32_e32 v16, v116, v20
	v_fmac_f32_e32 v24, v124, v28
	v_fmac_f32_e32 v0, v117, v5
	v_fmac_f32_e32 v8, v125, v13
	v_med3_f32 v22, v22, 0, v192
	v_med3_f32 v30, v30, 0, v192
	v_med3_f32 v7, v7, 0, v192
	v_med3_f32 v15, v15, 0, v192
	v_fmac_f32_e32 v16, v117, v21
	v_fmac_f32_e32 v24, v125, v29
	v_fmac_f32_e32 v0, v118, v6
	v_fmac_f32_e32 v8, v126, v14
	v_med3_f32 v23, v23, 0, v192
	v_med3_f32 v31, v31, 0, v192
	v_fmac_f32_e32 v16, v118, v22
	v_fmac_f32_e32 v24, v126, v30
	v_fmac_f32_e32 v0, v119, v7
	v_fmac_f32_e32 v8, v127, v15
	v_fmac_f32_e32 v16, v119, v23
	v_fmac_f32_e32 v24, v127, v31
	ds_bpermute_b32 v1, v196, v0
	ds_bpermute_b32 v2, v196, v8
	ds_bpermute_b32 v3, v196, v16
	ds_bpermute_b32 v4, v196, v24
	s_waitcnt lgkmcnt(3)
	v_add_f32_e32 v0, v0, v1
	s_waitcnt lgkmcnt(2)
	v_add_f32_e32 v1, v8, v2
	s_waitcnt lgkmcnt(1)
	v_add_f32_e32 v2, v16, v3
	s_waitcnt lgkmcnt(0)
	v_add_f32_e32 v3, v24, v4
	v_cndmask_b32_e32 v0, v1, v0, vcc
	v_cndmask_b32_e32 v1, v3, v2, vcc
	v_cvt_f16_f32_e32 v0, v0
	v_cvt_f16_f32_e32 v1, v1
	global_store_short v[128:129], v0, off
	global_store_short v[128:129], v1, off offset:64
	v_lshl_add_u64 v[128:129], v[128:129], 0, s[90:91]
	s_cbranch_scc1 .LBB0_738
	v_add_u32_e32 v0, s4, v198
	v_ashrrev_i32_e32 v1, 31, v0
	v_lshlrev_b64 v[0:1], 13, v[0:1]
	v_lshl_add_u64 v[96:97], v[174:175], 0, v[0:1]
	s_mov_b32 s8, 0
	v_mov_b32_e32 v98, v181
.LBB0_740:
	ds_read_b128 v[0:3], v98
	ds_read_b128 v[16:19], v98 offset:4608
	ds_read_b128 v[100:103], v98 offset:16
	ds_read_b128 v[212:215], v98 offset:4624
	ds_read_b128 v[216:219], v98 offset:32
	ds_read_b128 v[220:223], v98 offset:4640
	ds_read_b128 v[224:227], v98 offset:48
	ds_read_b128 v[228:231], v98 offset:4656
	v_add_u32_e32 v98, 0x2400, v98
	s_add_i32 s8, s8, 2
	s_cmp_lt_i32 s8, s1
	s_waitcnt lgkmcnt(7)
	v_mfma_f32_32x32x16_bf16 v[0:15], v[64:67], v[0:3], 0
	s_waitcnt lgkmcnt(6)
	v_mfma_f32_32x32x16_bf16 v[16:31], v[64:67], v[16:19], 0
	s_waitcnt lgkmcnt(5)
	v_mfma_f32_32x32x16_bf16 v[0:15], v[68:71], v[100:103], v[0:15]
	s_waitcnt lgkmcnt(4)
	v_mfma_f32_32x32x16_bf16 v[16:31], v[68:71], v[212:215], v[16:31]
	s_waitcnt lgkmcnt(3)
	v_mfma_f32_32x32x16_bf16 v[0:15], v[72:75], v[216:219], v[0:15]
	s_waitcnt lgkmcnt(2)
	v_mfma_f32_32x32x16_bf16 v[16:31], v[72:75], v[220:223], v[16:31]
	s_waitcnt lgkmcnt(1)
	v_mfma_f32_32x32x16_bf16 v[0:15], v[76:79], v[224:227], v[0:15]
	s_waitcnt lgkmcnt(0)
	v_mfma_f32_32x32x16_bf16 v[16:31], v[76:79], v[228:231], v[16:31]
	s_nop 9
	v_med3_f32 v0, v0, 0, v192
	v_med3_f32 v8, v8, 0, v192
	v_med3_f32 v1, v1, 0, v192
	v_med3_f32 v9, v9, 0, v192
	v_fma_f32 v0, v80, v0, 0
	v_fma_f32 v8, v88, v8, 0
	v_med3_f32 v2, v2, 0, v192
	v_med3_f32 v16, v16, 0, v192
	v_med3_f32 v24, v24, 0, v192
	v_med3_f32 v17, v17, 0, v192
	v_med3_f32 v25, v25, 0, v192
	v_med3_f32 v10, v10, 0, v192
	v_fma_f32 v16, v80, v16, 0
	v_fma_f32 v24, v88, v24, 0
	v_fmac_f32_e32 v0, v81, v1
	v_fmac_f32_e32 v8, v89, v9
	v_med3_f32 v18, v18, 0, v192
	v_med3_f32 v26, v26, 0, v192
	v_med3_f32 v3, v3, 0, v192
	v_med3_f32 v11, v11, 0, v192
	v_fmac_f32_e32 v16, v81, v17
	v_fmac_f32_e32 v24, v89, v25
	v_fmac_f32_e32 v0, v82, v2
	v_fmac_f32_e32 v8, v90, v10
	v_med3_f32 v19, v19, 0, v192
	v_med3_f32 v27, v27, 0, v192
	v_med3_f32 v4, v4, 0, v192
	v_med3_f32 v12, v12, 0, v192
	v_fmac_f32_e32 v16, v82, v18
	v_fmac_f32_e32 v24, v90, v26
	v_fmac_f32_e32 v0, v83, v3
	v_fmac_f32_e32 v8, v91, v11
	v_med3_f32 v20, v20, 0, v192
	v_med3_f32 v28, v28, 0, v192
	v_med3_f32 v5, v5, 0, v192
	v_med3_f32 v13, v13, 0, v192
	v_fmac_f32_e32 v16, v83, v19
	v_fmac_f32_e32 v24, v91, v27
	v_fmac_f32_e32 v0, v84, v4
	v_fmac_f32_e32 v8, v92, v12
	v_med3_f32 v21, v21, 0, v192
	v_med3_f32 v29, v29, 0, v192
	v_med3_f32 v6, v6, 0, v192
	v_med3_f32 v14, v14, 0, v192
	v_fmac_f32_e32 v16, v84, v20
	v_fmac_f32_e32 v24, v92, v28
	v_fmac_f32_e32 v0, v85, v5
	v_fmac_f32_e32 v8, v93, v13
	v_med3_f32 v22, v22, 0, v192
	v_med3_f32 v30, v30, 0, v192
	v_med3_f32 v7, v7, 0, v192
	v_med3_f32 v15, v15, 0, v192
	v_fmac_f32_e32 v16, v85, v21
	v_fmac_f32_e32 v24, v93, v29
	v_fmac_f32_e32 v0, v86, v6
	v_fmac_f32_e32 v8, v94, v14
	v_med3_f32 v23, v23, 0, v192
	v_med3_f32 v31, v31, 0, v192
	v_fmac_f32_e32 v16, v86, v22
	v_fmac_f32_e32 v24, v94, v30
	v_fmac_f32_e32 v0, v87, v7
	v_fmac_f32_e32 v8, v95, v15
	v_fmac_f32_e32 v16, v87, v23
	v_fmac_f32_e32 v24, v95, v31
	ds_bpermute_b32 v1, v196, v0
	ds_bpermute_b32 v2, v196, v8
	ds_bpermute_b32 v3, v196, v16
	ds_bpermute_b32 v4, v196, v24
	s_waitcnt lgkmcnt(3)
	v_add_f32_e32 v0, v0, v1
	s_waitcnt lgkmcnt(2)
	v_add_f32_e32 v1, v8, v2
	s_waitcnt lgkmcnt(1)
	v_add_f32_e32 v2, v16, v3
	s_waitcnt lgkmcnt(0)
	v_add_f32_e32 v3, v24, v4
	v_cndmask_b32_e32 v0, v1, v0, vcc
	v_cndmask_b32_e32 v1, v3, v2, vcc
	v_cvt_f16_f32_e32 v0, v0
	v_cvt_f16_f32_e32 v1, v1
	global_store_short v[96:97], v0, off
	global_store_short v[96:97], v1, off offset:64
	v_lshl_add_u64 v[96:97], v[96:97], 0, s[90:91]
	s_cbranch_scc1 .LBB0_740
	v_add_u32_e32 v0, s4, v197
	v_ashrrev_i32_e32 v1, 31, v0
	v_lshlrev_b64 v[0:1], 13, v[0:1]
	v_lshl_add_u64 v[64:65], v[174:175], 0, v[0:1]
	s_mov_b32 s4, 0
	v_mov_b32_e32 v66, v181
; #define LAS __attribute__((address_space(3)))
; __device__ __forceinline__ float relu1(float a) { return __builtin_amdgcn_fmed3f(a, 0.f, 3.0e38f); }
; __device__ __forceinline__ void idx_phase(const int TID, const int BID, PP p, LAS unsigned char* lds) {
;     ...
;                 bf16x8 Bf0[4], Bf1[4];
; #pragma unroll
;                 for (int ks = 0; ks < 4; ++ks) { Bf0[ks] = *(const LAS bf16x8*)(lds + (kt * 32 + rr) * 144 + g2 * 64 + ks * 16); Bf1[ks] = *(const LAS bf16x8*)(lds + ((kt + 1) * 32 + rr) * 144 + g2 * 64 + ks * 16); }
; #pragma unroll
;                 for (int ks = 0; ks < 4; ++ks) { acc0 = __builtin_amdgcn_mfma_f32_32x32x16_bf16(A[ks], Bf0[ks], acc0, 0, 0, 0); acc1 = __builtin_amdgcn_mfma_f32_32x32x16_bf16(A[ks], Bf1[ks], acc1, 0, 0, 0); }
;                 float s0 = 0.f, s1 = 0.f, t0 = 0.f, t1 = 0.f;
; #pragma unroll
;                 for (int i = 0; i < 8; ++i) { s0 += relu1(acc0[i]) * wq[i]; s1 += relu1(acc0[8 + i]) * wq[8 + i]; t0 += relu1(acc1[i]) * wq[i]; t1 += relu1(acc1[8 + i]) * wq[8 + i]; }
;                 s0 += __shfl_xor(s0, 32); s1 += __shfl_xor(s1, 32); t0 += __shfl_xor(t0, 32); t1 += __shfl_xor(t1, 32);
;                 _Float16* so = Sc + (size_t)(tokq + g2) * SEQ + key0 + kt * 32 + rr;
;                 so[0] = (_Float16)(g2 ? s1 : s0); so[32] = (_Float16)(g2 ? t1 : t0);
.LBB0_742:
	ds_read_b128 v[0:3], v66
	ds_read_b128 v[16:19], v66 offset:4608
	ds_read_b128 v[68:71], v66 offset:16
	ds_read_b128 v[212:215], v66 offset:4624
	ds_read_b128 v[216:219], v66 offset:32
	ds_read_b128 v[220:223], v66 offset:4640
	ds_read_b128 v[224:227], v66 offset:48
	ds_read_b128 v[228:231], v66 offset:4656
	v_add_u32_e32 v66, 0x2400, v66
	s_add_i32 s4, s4, 2
	s_cmp_lt_i32 s4, s1
	s_waitcnt lgkmcnt(7)
	v_mfma_f32_32x32x16_bf16 v[0:15], v[32:35], v[0:3], 0
	s_waitcnt lgkmcnt(6)
	v_mfma_f32_32x32x16_bf16 v[16:31], v[32:35], v[16:19], 0
	s_waitcnt lgkmcnt(5)
	v_mfma_f32_32x32x16_bf16 v[0:15], v[36:39], v[68:71], v[0:15]
	s_waitcnt lgkmcnt(4)
	v_mfma_f32_32x32x16_bf16 v[16:31], v[36:39], v[212:215], v[16:31]
	s_waitcnt lgkmcnt(3)
	v_mfma_f32_32x32x16_bf16 v[0:15], v[40:43], v[216:219], v[0:15]
	s_waitcnt lgkmcnt(2)
	v_mfma_f32_32x32x16_bf16 v[16:31], v[40:43], v[220:223], v[16:31]
	s_waitcnt lgkmcnt(1)
	v_mfma_f32_32x32x16_bf16 v[0:15], v[44:47], v[224:227], v[0:15]
	s_waitcnt lgkmcnt(0)
	v_mfma_f32_32x32x16_bf16 v[16:31], v[44:47], v[228:231], v[16:31]
	s_nop 9
	v_med3_f32 v0, v0, 0, v192
	v_med3_f32 v8, v8, 0, v192
	v_med3_f32 v1, v1, 0, v192
	v_med3_f32 v9, v9, 0, v192
	v_fma_f32 v0, v48, v0, 0
	v_fma_f32 v8, v56, v8, 0
	v_med3_f32 v2, v2, 0, v192
	v_med3_f32 v16, v16, 0, v192
	v_med3_f32 v24, v24, 0, v192
	v_med3_f32 v17, v17, 0, v192
	v_med3_f32 v25, v25, 0, v192
	v_med3_f32 v10, v10, 0, v192
	v_fma_f32 v16, v48, v16, 0
	v_fma_f32 v24, v56, v24, 0
	v_fmac_f32_e32 v0, v49, v1
	v_fmac_f32_e32 v8, v57, v9
	v_med3_f32 v18, v18, 0, v192
	v_med3_f32 v26, v26, 0, v192
	v_med3_f32 v3, v3, 0, v192
	v_med3_f32 v11, v11, 0, v192
	v_fmac_f32_e32 v16, v49, v17
	v_fmac_f32_e32 v24, v57, v25
	v_fmac_f32_e32 v0, v50, v2
	v_fmac_f32_e32 v8, v58, v10
	v_med3_f32 v19, v19, 0, v192
	v_med3_f32 v27, v27, 0, v192
	v_med3_f32 v4, v4, 0, v192
	v_med3_f32 v12, v12, 0, v192
	v_fmac_f32_e32 v16, v50, v18
	v_fmac_f32_e32 v24, v58, v26
	v_fmac_f32_e32 v0, v51, v3
	v_fmac_f32_e32 v8, v59, v11
	v_med3_f32 v20, v20, 0, v192
	v_med3_f32 v28, v28, 0, v192
	v_med3_f32 v5, v5, 0, v192
	v_med3_f32 v13, v13, 0, v192
	v_fmac_f32_e32 v16, v51, v19
	v_fmac_f32_e32 v24, v59, v27
	v_fmac_f32_e32 v0, v52, v4
	v_fmac_f32_e32 v8, v60, v12
	v_med3_f32 v21, v21, 0, v192
	v_med3_f32 v29, v29, 0, v192
	v_med3_f32 v6, v6, 0, v192
	v_med3_f32 v14, v14, 0, v192
	v_fmac_f32_e32 v16, v52, v20
	v_fmac_f32_e32 v24, v60, v28
	v_fmac_f32_e32 v0, v53, v5
	v_fmac_f32_e32 v8, v61, v13
	v_med3_f32 v22, v22, 0, v192
	v_med3_f32 v30, v30, 0, v192
	v_med3_f32 v7, v7, 0, v192
	v_med3_f32 v15, v15, 0, v192
	v_fmac_f32_e32 v16, v53, v21
	v_fmac_f32_e32 v24, v61, v29
	v_fmac_f32_e32 v0, v54, v6
	v_fmac_f32_e32 v8, v62, v14
	v_med3_f32 v23, v23, 0, v192
	v_med3_f32 v31, v31, 0, v192
	v_fmac_f32_e32 v16, v54, v22
	v_fmac_f32_e32 v24, v62, v30
	v_fmac_f32_e32 v0, v55, v7
	v_fmac_f32_e32 v8, v63, v15
	v_fmac_f32_e32 v16, v55, v23
	v_fmac_f32_e32 v24, v63, v31
	ds_bpermute_b32 v1, v196, v0
	ds_bpermute_b32 v2, v196, v8
	ds_bpermute_b32 v3, v196, v16
	ds_bpermute_b32 v4, v196, v24
	s_waitcnt lgkmcnt(3)
	v_add_f32_e32 v0, v0, v1
	s_waitcnt lgkmcnt(2)
	v_add_f32_e32 v1, v8, v2
	s_waitcnt lgkmcnt(1)
	v_add_f32_e32 v2, v16, v3
	s_waitcnt lgkmcnt(0)
	v_add_f32_e32 v3, v24, v4
	v_cndmask_b32_e32 v0, v1, v0, vcc
	v_cndmask_b32_e32 v1, v3, v2, vcc
	v_cvt_f16_f32_e32 v0, v0
	v_cvt_f16_f32_e32 v1, v1
	global_store_short v[64:65], v0, off
	global_store_short v[64:65], v1, off offset:64
	v_lshl_add_u64 v[64:65], v[64:65], 0, s[90:91]
	s_cbranch_scc1 .LBB0_742
	s_branch .LBB0_729

; __device__ __forceinline__ float rinv_st(stat_t s, float invn) { return rsqrtf((float)((double)s * (1.0 / 4294967296.0)) * invn + 1e-6f); }
; template <class Epi>
; __device__ __forceinline__ void gemm_phase(const int TID, const int BID, LAS unsigned char* lds, const Gemm g, const StaticOrder& S, const Epi& E) {
;     ...
;         const bool has_next = S.next(ui + 1, nxt);
;         const char* nA = has_next ? (const char*)g.A + (size_t)nxt.pm * tstepA : cA; const char* nB = has_next ? (const char*)g.Bt + (size_t)nxt.pn * tstepB : cB;
;     __device__ __forceinline__ void operator()(const f32x4 (&acc)[2][2][4][2], const Unit& u, int wr, int wc, int fr, int fq) const {
;         const int row0 = u.pm * BM + wr * 64 + fr, col0 = u.pn * BM + wc * 32 + 8 * fq;
; #pragma unroll
;         for (int ai = 0; ai < 2; ++ai)
; #pragma unroll
;             for (int m = 0; m < 4; ++m) {
;                 const int row = row0 + ai * HALF + m * 16; const float r = rinv_st(stats[row], 1.0f / 2048.0f);
.LBB0_918:
	v_lshl_add_u32 v252, s30, 8, v146
	v_ashrrev_i32_e32 v253, 31, v252
	v_lshl_add_u64 v[252:253], v[252:253], 3, s[10:11]
	global_load_dwordx2 v[236:237], v[252:253], off
	global_load_dwordx2 v[238:239], v[252:253], off offset:128
	global_load_dwordx2 v[240:241], v[252:253], off offset:256
	global_load_dwordx2 v[242:243], v[252:253], off offset:384
	global_load_dwordx2 v[244:245], v[252:253], off offset:1024
	global_load_dwordx2 v[246:247], v[252:253], off offset:1152
	global_load_dwordx2 v[248:249], v[252:253], off offset:1280
	global_load_dwordx2 v[250:251], v[252:253], off offset:1408
	s_add_i32 s63, s63, 1
	s_mul_i32 s1, s63, s65
	s_mul_hi_u32 s4, s63, s70
	s_add_i32 s4, s4, s1
	s_mul_i32 s1, s63, s70
	s_add_u32 s26, s1, s92
	s_addc_u32 s27, s4, s43
	v_mov_b64_e32 v[0:1], 0x3ff
	v_cmp_gt_i64_e64 s[8:9], s[26:27], v[0:1]
	s_and_b64 vcc, exec, s[8:9]
	s_cbranch_vccnz .LBB0_924
	s_ashr_i32 s1, s26, 31
	s_lshr_b32 s1, s1, 29
	s_add_i32 s1, s26, s1
	s_and_b32 s4, s1, -8
	s_sub_i32 s4, s26, s4
	s_cmp_gt_i32 s4, -1
	s_mov_b64 s[16:17], -1
	s_cbranch_scc0 .LBB0_921
	s_lshl_b32 s18, s4, 7
	s_mov_b64 s[16:17], 0

; #define PG8_STAGE(bufoff, gbase, voff) do { _Pragma("unroll") for (int _i = 0; _i < 2; ++_i) \
;         __builtin_amdgcn_global_load_lds((const unsigned*)((const char*)(gbase) + (voff)[_i]), (LAS unsigned*)(lds + (bufoff) + ldsw + _i * 8192), 16, 0, 0); } while (0)
; #define PG8_LDA(dst, b, h) do { _Pragma("unroll") for (int m = 0; m < 4; ++m) _Pragma("unroll") for (int k = 0; k < 2; ++k) dst[m][k] = *(const LAS bf16x8*)(lds + PG8_SA(b, h) + aoff + m * 2048 + k * 1024); } while (0)
; #define PG8_LDB(dst, b, h) do { _Pragma("unroll") for (int n = 0; n < 2; ++n) _Pragma("unroll") for (int k = 0; k < 2; ++k) dst[n][k] = *(const LAS bf16x8*)(lds + PG8_SB(b, h) + boff + n * 2048 + k * 1024); } while (0)
; #define PG8_MMA(ai, bj, At, Bt) do { __builtin_amdgcn_s_setprio(1); _Pragma("unroll") for (int m = 0; m < 4; ++m) _Pragma("unroll") for (int n = 0; n < 2; ++n) _Pragma("unroll") for (int k = 0; k < 2; ++k) \
;         acc[ai][bj][m][n] = __builtin_amdgcn_mfma_f32_16x16x32_bf16(Bt[n][k], At[m][k], acc[ai][bj][m][n], 0, 0, 0); __builtin_amdgcn_s_setprio(0); } while (0)
; #define PG8_WAIT_V(n) asm volatile("s_waitcnt vmcnt(" #n ")" ::: "memory")
; #define PG8_WAIT_L(n) asm volatile("s_waitcnt lgkmcnt(" #n ")" ::: "memory")
; #define PG8_BAR __builtin_amdgcn_s_barrier()
; #define PG8_SCHED __builtin_amdgcn_sched_barrier(0)
; template <class Epi>
; __device__ __forceinline__ void gemm_phase(const int TID, const int BID, LAS unsigned char* lds, const Gemm g, const StaticOrder& S, const Epi& E) {
;     ...
;             PG8_LDB(B0, 0, 0); PG8_SCHED; PG8_LDA(At, 0, 0); PG8_STAGE(PG8_SA(1, 1), a1 + hstepA, voffA);
;             PG8_WAIT_L(8); PG8_BAR; PG8_WAIT_L(0); PG8_MMA(0, 0, At, B0); PG8_BAR; PG8_SCHED;
;             PG8_LDB(B1, 0, 1); PG8_STAGE(PG8_SB(0, 0), b2, voffB);
;             PG8_BAR; PG8_WAIT_L(0); PG8_MMA(0, 1, At, B1); PG8_BAR;
;             PG8_LDA(At, 0, 1); PG8_STAGE(PG8_SA(0, 0), a2, voffA);
;             PG8_BAR; PG8_WAIT_L(0); PG8_MMA(1, 0, At, B0); PG8_BAR; PG8_SCHED;
;             PG8_STAGE(PG8_SB(0, 1), b2 + hstepB, voffB);
;             PG8_WAIT_V(6); PG8_BAR; PG8_MMA(1, 1, At, B1); PG8_BAR;
.LBB0_925:
	v_add_u32_e32 v154, s31, v147
	ds_read_b128 v[138:141], v154
	ds_read_b128 v[142:145], v154 offset:1024
	ds_read_b128 v[150:153], v154 offset:2048
	ds_read_b128 v[154:157], v154 offset:3072
	s_add_u32 s36, s34, 0xfff80080
	s_addc_u32 s37, s35, -1
	s_cmp_eq_u32 s64, 28
	s_cselect_b32 s39, s1, s37
	s_cselect_b32 s38, s4, s36
	s_cselect_b32 s37, s17, s23
	s_cselect_b32 s36, s19, s22
	v_lshl_add_u64 v[158:159], s[34:35], 0, v[134:135]
	s_add_i32 m0, s48, 0xc000
	ds_read_b128 v[166:169], v149
	ds_read_b128 v[170:173], v149 offset:1024
	ds_read_b128 v[174:177], v149 offset:2048
	ds_read_b128 v[178:181], v149 offset:3072
	ds_read_b128 v[182:185], v149 offset:4096
	ds_read_b128 v[196:199], v149 offset:5120
	ds_read_b128 v[208:211], v149 offset:6144
	ds_read_b128 v[212:215], v149 offset:7168
	global_load_lds_dwordx4 v[158:159], off
	v_lshl_add_u64 v[158:159], s[34:35], 0, v[136:137]
	s_add_i32 m0, s48, 0xe000
	s_nop 0
	global_load_lds_dwordx4 v[158:159], off
	s_waitcnt lgkmcnt(8)
	s_barrier
	s_waitcnt lgkmcnt(0)
	s_setprio 1
	s_waitcnt lgkmcnt(0)
	v_mfma_f32_16x16x32_bf16 v[124:127], v[138:141], v[166:169], v[124:127]
	v_mfma_f32_16x16x32_bf16 v[120:123], v[150:153], v[166:169], v[120:123]
	v_mfma_f32_16x16x32_bf16 v[108:111], v[138:141], v[174:177], v[108:111]
	v_mfma_f32_16x16x32_bf16 v[104:107], v[150:153], v[174:177], v[104:107]
	v_mfma_f32_16x16x32_bf16 v[92:95], v[138:141], v[182:185], v[92:95]
	v_mfma_f32_16x16x32_bf16 v[88:91], v[150:153], v[182:185], v[88:91]
	v_mfma_f32_16x16x32_bf16 v[76:79], v[138:141], v[208:211], v[76:79]
	v_mfma_f32_16x16x32_bf16 v[72:75], v[150:153], v[208:211], v[72:75]
	v_mfma_f32_16x16x32_bf16 v[124:127], v[142:145], v[170:173], v[124:127]
	v_mfma_f32_16x16x32_bf16 v[120:123], v[154:157], v[170:173], v[120:123]
	v_mfma_f32_16x16x32_bf16 v[108:111], v[142:145], v[178:181], v[108:111]
	v_mfma_f32_16x16x32_bf16 v[104:107], v[154:157], v[178:181], v[104:107]
	v_mfma_f32_16x16x32_bf16 v[92:95], v[142:145], v[196:199], v[92:95]
	v_mfma_f32_16x16x32_bf16 v[88:91], v[154:157], v[196:199], v[88:91]
	v_mfma_f32_16x16x32_bf16 v[76:79], v[142:145], v[212:215], v[76:79]
	v_mfma_f32_16x16x32_bf16 v[72:75], v[154:157], v[212:215], v[72:75]
	s_setprio 0
	s_barrier
	v_add_u32_e32 v158, s50, v147
	s_mov_b32 m0, s46
	ds_read_b128 v[216:219], v158
	ds_read_b128 v[220:223], v158 offset:1024
	ds_read_b128 v[224:227], v158 offset:2048
	ds_read_b128 v[228:231], v158 offset:3072
	v_lshl_add_u64 v[158:159], s[36:37], 0, v[160:161]
	global_load_lds_dwordx4 v[158:159], off
	v_lshl_add_u64 v[200:201], s[36:37], 0, v[132:133]
	s_mov_b32 m0, s47
	s_nop 0
	global_load_lds_dwordx4 v[200:201], off
	s_barrier
	s_waitcnt lgkmcnt(0)
	s_setprio 1
	s_waitcnt lgkmcnt(0)
	v_mfma_f32_16x16x32_bf16 v[116:119], v[216:219], v[166:169], v[116:119]
	v_mfma_f32_16x16x32_bf16 v[112:115], v[224:227], v[166:169], v[112:115]
	v_mfma_f32_16x16x32_bf16 v[100:103], v[216:219], v[174:177], v[100:103]
	v_mfma_f32_16x16x32_bf16 v[96:99], v[224:227], v[174:177], v[96:99]
	v_mfma_f32_16x16x32_bf16 v[84:87], v[216:219], v[182:185], v[84:87]
	v_mfma_f32_16x16x32_bf16 v[80:83], v[224:227], v[182:185], v[80:83]
	v_mfma_f32_16x16x32_bf16 v[68:71], v[216:219], v[208:211], v[68:71]
	v_mfma_f32_16x16x32_bf16 v[64:67], v[224:227], v[208:211], v[64:67]
	v_mfma_f32_16x16x32_bf16 v[116:119], v[220:223], v[170:173], v[116:119]
	v_mfma_f32_16x16x32_bf16 v[112:115], v[228:231], v[170:173], v[112:115]
	v_mfma_f32_16x16x32_bf16 v[100:103], v[220:223], v[178:181], v[100:103]
	v_mfma_f32_16x16x32_bf16 v[96:99], v[228:231], v[178:181], v[96:99]
	v_mfma_f32_16x16x32_bf16 v[84:87], v[220:223], v[196:199], v[84:87]
	v_mfma_f32_16x16x32_bf16 v[80:83], v[228:231], v[196:199], v[80:83]
	v_mfma_f32_16x16x32_bf16 v[68:71], v[220:223], v[212:215], v[68:71]
	v_mfma_f32_16x16x32_bf16 v[64:67], v[228:231], v[212:215], v[64:67]
	s_setprio 0
	s_mov_b32 m0, s48
	v_lshl_add_u64 v[232:233], s[38:39], 0, v[128:129]
	s_barrier
	ds_read_b128 v[166:169], v149 offset:16384
	ds_read_b128 v[170:173], v149 offset:17408
	ds_read_b128 v[174:177], v149 offset:18432
	ds_read_b128 v[178:181], v149 offset:19456
	ds_read_b128 v[182:185], v149 offset:20480
	ds_read_b128 v[196:199], v149 offset:21504
	ds_read_b128 v[208:211], v149 offset:22528
	ds_read_b128 v[212:215], v149 offset:23552
	global_load_lds_dwordx4 v[232:233], off
	v_lshl_add_u64 v[234:235], s[38:39], 0, v[130:131]
	s_mov_b32 m0, s49
	s_nop 0
	global_load_lds_dwordx4 v[234:235], off
	s_barrier
	s_waitcnt lgkmcnt(0)
	s_setprio 1
	s_waitcnt lgkmcnt(0)
	v_mfma_f32_16x16x32_bf16 v[60:63], v[138:141], v[166:169], v[60:63]
	v_mfma_f32_16x16x32_bf16 v[56:59], v[150:153], v[166:169], v[56:59]
	v_mfma_f32_16x16x32_bf16 v[44:47], v[138:141], v[174:177], v[44:47]
	v_mfma_f32_16x16x32_bf16 v[40:43], v[150:153], v[174:177], v[40:43]
	v_mfma_f32_16x16x32_bf16 v[28:31], v[138:141], v[182:185], v[28:31]
	v_mfma_f32_16x16x32_bf16 v[24:27], v[150:153], v[182:185], v[24:27]
	v_mfma_f32_16x16x32_bf16 v[12:15], v[138:141], v[208:211], v[12:15]
	v_mfma_f32_16x16x32_bf16 v[8:11], v[150:153], v[208:211], v[8:11]
	v_mfma_f32_16x16x32_bf16 v[60:63], v[142:145], v[170:173], v[60:63]
	v_mfma_f32_16x16x32_bf16 v[56:59], v[154:157], v[170:173], v[56:59]
	v_mfma_f32_16x16x32_bf16 v[44:47], v[142:145], v[178:181], v[44:47]
	v_mfma_f32_16x16x32_bf16 v[40:43], v[154:157], v[178:181], v[40:43]
	v_mfma_f32_16x16x32_bf16 v[28:31], v[142:145], v[196:199], v[28:31]
	v_mfma_f32_16x16x32_bf16 v[24:27], v[154:157], v[196:199], v[24:27]
	v_mfma_f32_16x16x32_bf16 v[12:15], v[142:145], v[212:215], v[12:15]
	v_mfma_f32_16x16x32_bf16 v[8:11], v[154:157], v[212:215], v[8:11]
	s_setprio 0
	s_barrier
; #define PG8_STAGE(bufoff, gbase, voff) do { _Pragma("unroll") for (int _i = 0; _i < 2; ++_i) \
;         __builtin_amdgcn_global_load_lds((const unsigned*)((const char*)(gbase) + (voff)[_i]), (LAS unsigned*)(lds + (bufoff) + ldsw + _i * 8192), 16, 0, 0); } while (0)
; #define PG8_LDA(dst, b, h) do { _Pragma("unroll") for (int m = 0; m < 4; ++m) _Pragma("unroll") for (int k = 0; k < 2; ++k) dst[m][k] = *(const LAS bf16x8*)(lds + PG8_SA(b, h) + aoff + m * 2048 + k * 1024); } while (0)
; #define PG8_LDB(dst, b, h) do { _Pragma("unroll") for (int n = 0; n < 2; ++n) _Pragma("unroll") for (int k = 0; k < 2; ++k) dst[n][k] = *(const LAS bf16x8*)(lds + PG8_SB(b, h) + boff + n * 2048 + k * 1024); } while (0)
; #define PG8_MMA(ai, bj, At, Bt) do { __builtin_amdgcn_s_setprio(1); _Pragma("unroll") for (int m = 0; m < 4; ++m) _Pragma("unroll") for (int n = 0; n < 2; ++n) _Pragma("unroll") for (int k = 0; k < 2; ++k) \
;         acc[ai][bj][m][n] = __builtin_amdgcn_mfma_f32_16x16x32_bf16(Bt[n][k], At[m][k], acc[ai][bj][m][n], 0, 0, 0); __builtin_amdgcn_s_setprio(0); } while (0)
; #define PG8_WAIT_V(n) asm volatile("s_waitcnt vmcnt(" #n ")" ::: "memory")
; #define PG8_WAIT_L(n) asm volatile("s_waitcnt lgkmcnt(" #n ")" ::: "memory")
; #define PG8_BAR __builtin_amdgcn_s_barrier()
; #define PG8_SCHED __builtin_amdgcn_sched_barrier(0)
; template <class Epi>
; __device__ __forceinline__ void gemm_phase(const int TID, const int BID, LAS unsigned char* lds, const Gemm g, const StaticOrder& S, const Epi& E) {
;     ...
;             PG8_WAIT_V(6); PG8_BAR; PG8_MMA(1, 1, At, B1); PG8_BAR;
;             PG8_LDB(B0, 1, 0); PG8_SCHED; PG8_LDA(At, 1, 0); PG8_STAGE(PG8_SA(0, 1), a2 + hstepA, voffA);
;             PG8_WAIT_L(8); PG8_BAR; PG8_WAIT_L(0); PG8_MMA(0, 0, At, B0); PG8_BAR; PG8_SCHED;
;             PG8_LDB(B1, 1, 1); PG8_STAGE(PG8_SB(1, 0), b3, voffB);
;             PG8_BAR; PG8_WAIT_L(0); PG8_MMA(0, 1, At, B1); PG8_BAR;
;             PG8_LDA(At, 1, 1); PG8_STAGE(PG8_SA(1, 0), a3, voffA);
;             PG8_BAR; PG8_WAIT_L(0); PG8_MMA(1, 0, At, B0); PG8_BAR; PG8_SCHED;
	s_add_u32 s66, s36, 0x80000
	s_addc_u32 s67, s37, 0
	s_mov_b32 m0, s51
	v_lshl_add_u64 v[138:139], s[66:67], 0, v[160:161]
	global_load_lds_dwordx4 v[138:139], off
	v_lshl_add_u64 v[138:139], s[66:67], 0, v[132:133]
	s_mov_b32 m0, s52
	s_nop 0
	global_load_lds_dwordx4 v[138:139], off
	s_waitcnt vmcnt(6)
	s_barrier
	s_setprio 1
	v_mfma_f32_16x16x32_bf16 v[52:55], v[216:219], v[166:169], v[52:55]
	v_mfma_f32_16x16x32_bf16 v[48:51], v[224:227], v[166:169], v[48:51]
	v_mfma_f32_16x16x32_bf16 v[36:39], v[216:219], v[174:177], v[36:39]
	v_mfma_f32_16x16x32_bf16 v[32:35], v[224:227], v[174:177], v[32:35]
	v_mfma_f32_16x16x32_bf16 v[20:23], v[216:219], v[182:185], v[20:23]
	v_mfma_f32_16x16x32_bf16 v[16:19], v[224:227], v[182:185], v[16:19]
	v_mfma_f32_16x16x32_bf16 v[4:7], v[216:219], v[208:211], v[4:7]
	v_mfma_f32_16x16x32_bf16 v[0:3], v[224:227], v[208:211], v[0:3]
	v_mfma_f32_16x16x32_bf16 v[52:55], v[220:223], v[170:173], v[52:55]
	v_mfma_f32_16x16x32_bf16 v[48:51], v[228:231], v[170:173], v[48:51]
	v_mfma_f32_16x16x32_bf16 v[36:39], v[220:223], v[178:181], v[36:39]
	v_mfma_f32_16x16x32_bf16 v[32:35], v[228:231], v[178:181], v[32:35]
	v_mfma_f32_16x16x32_bf16 v[20:23], v[220:223], v[196:199], v[20:23]
	v_mfma_f32_16x16x32_bf16 v[16:19], v[228:231], v[196:199], v[16:19]
	v_mfma_f32_16x16x32_bf16 v[4:7], v[220:223], v[212:215], v[4:7]
	v_mfma_f32_16x16x32_bf16 v[0:3], v[228:231], v[212:215], v[0:3]
	s_setprio 0
	v_add_u32_e32 v154, s55, v147
	s_barrier
	ds_read_b128 v[138:141], v154
	ds_read_b128 v[142:145], v154 offset:1024
	ds_read_b128 v[150:153], v154 offset:2048
	ds_read_b128 v[154:157], v154 offset:3072
	s_add_u32 s38, s38, 0x80000
	s_addc_u32 s39, s39, 0
	s_mov_b32 m0, s53
	v_lshl_add_u64 v[216:217], s[38:39], 0, v[128:129]
	ds_read_b128 v[166:169], v149 offset:32768
	ds_read_b128 v[170:173], v149 offset:33792
	ds_read_b128 v[174:177], v149 offset:34816
	ds_read_b128 v[178:181], v149 offset:35840
	ds_read_b128 v[182:185], v149 offset:36864
	ds_read_b128 v[196:199], v149 offset:37888
	ds_read_b128 v[208:211], v149 offset:38912
	ds_read_b128 v[212:215], v149 offset:39936
	global_load_lds_dwordx4 v[216:217], off
	v_lshl_add_u64 v[216:217], s[38:39], 0, v[130:131]
	s_mov_b32 m0, s54
	s_nop 0
	global_load_lds_dwordx4 v[216:217], off
	s_waitcnt lgkmcnt(8)
	s_barrier
	s_waitcnt lgkmcnt(0)
	s_setprio 1
	s_waitcnt lgkmcnt(0)
	v_mfma_f32_16x16x32_bf16 v[124:127], v[138:141], v[166:169], v[124:127]
	v_mfma_f32_16x16x32_bf16 v[120:123], v[150:153], v[166:169], v[120:123]
	v_mfma_f32_16x16x32_bf16 v[108:111], v[138:141], v[174:177], v[108:111]
	v_mfma_f32_16x16x32_bf16 v[104:107], v[150:153], v[174:177], v[104:107]
	v_mfma_f32_16x16x32_bf16 v[92:95], v[138:141], v[182:185], v[92:95]
	v_mfma_f32_16x16x32_bf16 v[88:91], v[150:153], v[182:185], v[88:91]
	v_mfma_f32_16x16x32_bf16 v[76:79], v[138:141], v[208:211], v[76:79]
	v_mfma_f32_16x16x32_bf16 v[72:75], v[150:153], v[208:211], v[72:75]
	v_mfma_f32_16x16x32_bf16 v[124:127], v[142:145], v[170:173], v[124:127]
	v_mfma_f32_16x16x32_bf16 v[120:123], v[154:157], v[170:173], v[120:123]
	v_mfma_f32_16x16x32_bf16 v[108:111], v[142:145], v[178:181], v[108:111]
	v_mfma_f32_16x16x32_bf16 v[104:107], v[154:157], v[178:181], v[104:107]
	v_mfma_f32_16x16x32_bf16 v[92:95], v[142:145], v[196:199], v[92:95]
	v_mfma_f32_16x16x32_bf16 v[88:91], v[154:157], v[196:199], v[88:91]
	v_mfma_f32_16x16x32_bf16 v[76:79], v[142:145], v[212:215], v[76:79]
	v_mfma_f32_16x16x32_bf16 v[72:75], v[154:157], v[212:215], v[72:75]
	s_setprio 0
	s_barrier
	s_mov_b32 m0, s56
	v_add_u32_e32 v228, s60, v147
	v_lshl_add_u64 v[158:159], v[158:159], 0, s[90:91]
	ds_read_b128 v[216:219], v228
	ds_read_b128 v[220:223], v228 offset:1024
	ds_read_b128 v[224:227], v228 offset:2048
	ds_read_b128 v[228:231], v228 offset:3072
	global_load_lds_dwordx4 v[158:159], off
	v_lshl_add_u64 v[158:159], v[200:201], 0, s[90:91]
	s_mov_b32 m0, s57
	s_nop 0
	global_load_lds_dwordx4 v[158:159], off
	s_barrier
	s_waitcnt lgkmcnt(0)
	s_setprio 1
	s_waitcnt lgkmcnt(0)
	v_mfma_f32_16x16x32_bf16 v[116:119], v[216:219], v[166:169], v[116:119]
	v_mfma_f32_16x16x32_bf16 v[112:115], v[224:227], v[166:169], v[112:115]
	v_mfma_f32_16x16x32_bf16 v[100:103], v[216:219], v[174:177], v[100:103]
	v_mfma_f32_16x16x32_bf16 v[96:99], v[224:227], v[174:177], v[96:99]
	v_mfma_f32_16x16x32_bf16 v[84:87], v[216:219], v[182:185], v[84:87]
	v_mfma_f32_16x16x32_bf16 v[80:83], v[224:227], v[182:185], v[80:83]
	v_mfma_f32_16x16x32_bf16 v[68:71], v[216:219], v[208:211], v[68:71]
	v_mfma_f32_16x16x32_bf16 v[64:67], v[224:227], v[208:211], v[64:67]
	v_mfma_f32_16x16x32_bf16 v[116:119], v[220:223], v[170:173], v[116:119]
	v_mfma_f32_16x16x32_bf16 v[112:115], v[228:231], v[170:173], v[112:115]
	v_mfma_f32_16x16x32_bf16 v[100:103], v[220:223], v[178:181], v[100:103]
	v_mfma_f32_16x16x32_bf16 v[96:99], v[228:231], v[178:181], v[96:99]
	v_mfma_f32_16x16x32_bf16 v[84:87], v[220:223], v[196:199], v[84:87]
	v_mfma_f32_16x16x32_bf16 v[80:83], v[228:231], v[196:199], v[80:83]
	v_mfma_f32_16x16x32_bf16 v[68:71], v[220:223], v[212:215], v[68:71]
	v_mfma_f32_16x16x32_bf16 v[64:67], v[228:231], v[212:215], v[64:67]
	s_setprio 0
	s_mov_b32 m0, s58
	v_lshl_add_u64 v[158:159], v[232:233], 0, s[90:91]
	s_barrier
	ds_read_b128 v[166:169], v149 offset:49152
	ds_read_b128 v[170:173], v149 offset:50176
	ds_read_b128 v[174:177], v149 offset:51200
	ds_read_b128 v[178:181], v149 offset:52224
	ds_read_b128 v[182:185], v149 offset:53248
	ds_read_b128 v[196:199], v149 offset:54272
	ds_read_b128 v[208:211], v149 offset:55296
	ds_read_b128 v[212:215], v149 offset:56320
	global_load_lds_dwordx4 v[158:159], off
	v_lshl_add_u64 v[158:159], v[234:235], 0, s[90:91]
	s_mov_b32 m0, s59
	s_nop 0
	global_load_lds_dwordx4 v[158:159], off
	s_barrier
; __device__ __forceinline__ unsigned cvt_pk_bf16(float lo, float hi) { unsigned r; asm volatile("v_cvt_pk_bf16_f32 %0, %1, %2" : "=v"(r) : "v"(lo), "v"(hi)); return r; }
; __device__ __forceinline__ float rinv_st(stat_t s, float invn) { return rsqrtf((float)((double)s * (1.0 / 4294967296.0)) * invn + 1e-6f); }
; #define PG8_STAGE(bufoff, gbase, voff) do { _Pragma("unroll") for (int _i = 0; _i < 2; ++_i) \
;         __builtin_amdgcn_global_load_lds((const unsigned*)((const char*)(gbase) + (voff)[_i]), (LAS unsigned*)(lds + (bufoff) + ldsw + _i * 8192), 16, 0, 0); } while (0)
; #define PG8_MMA(ai, bj, At, Bt) do { __builtin_amdgcn_s_setprio(1); _Pragma("unroll") for (int m = 0; m < 4; ++m) _Pragma("unroll") for (int n = 0; n < 2; ++n) _Pragma("unroll") for (int k = 0; k < 2; ++k) \
;         acc[ai][bj][m][n] = __builtin_amdgcn_mfma_f32_16x16x32_bf16(Bt[n][k], At[m][k], acc[ai][bj][m][n], 0, 0, 0); __builtin_amdgcn_s_setprio(0); } while (0)
; #define PG8_WAIT_V(n) asm volatile("s_waitcnt vmcnt(" #n ")" ::: "memory")
; #define PG8_WAIT_L(n) asm volatile("s_waitcnt lgkmcnt(" #n ")" ::: "memory")
; #define PG8_BAR __builtin_amdgcn_s_barrier()
; template <class Epi>
; __device__ __forceinline__ void gemm_phase(const int TID, const int BID, LAS unsigned char* lds, const Gemm g, const StaticOrder& S, const Epi& E) {
;     ...
;             PG8_BAR; PG8_WAIT_L(0); PG8_MMA(1, 0, At, B0); PG8_BAR; PG8_SCHED;
;             PG8_STAGE(PG8_SB(1, 1), b3 + hstepB, voffB);
;             PG8_WAIT_V(6); PG8_BAR; PG8_MMA(1, 1, At, B1); PG8_BAR;
;         }
;     __device__ __forceinline__ void operator()(const f32x4 (&acc)[2][2][4][2], const Unit& u, int wr, int wc, int fr, int fq) const {
;     ...
;                 const int row = row0 + ai * HALF + m * 16; const float r = rinv_st(stats[row], 1.0f / 2048.0f);
;                 bf16_t* rowp = U + (size_t)row * FF + col0;
; #pragma unroll
;                 for (int bj = 0; bj < 2; ++bj) {
;                     f32x4 v0 = acc[ai][bj][m][0] * r, v1 = acc[ai][bj][m][1] * r;
; #pragma unroll
;                     for (int j = 0; j < 4; ++j) { const float a = fmaxf(v0[j], 0.f), b = fmaxf(v1[j], 0.f); v0[j] = a * a; v1[j] = b * b; }
;                     u32x4 w; w.x = cvt_pk_bf16(v0[0], v0[1]); w.y = cvt_pk_bf16(v0[2], v0[3]); w.z = cvt_pk_bf16(v1[0], v1[1]); w.w = cvt_pk_bf16(v1[2], v1[3]);
;                     *(u32x4*)(rowp + bj * HALF) = w;
	s_waitcnt lgkmcnt(0)
	s_setprio 1
	s_waitcnt lgkmcnt(0)
	v_mfma_f32_16x16x32_bf16 v[60:63], v[138:141], v[166:169], v[60:63]
	v_mfma_f32_16x16x32_bf16 v[56:59], v[150:153], v[166:169], v[56:59]
	v_mfma_f32_16x16x32_bf16 v[44:47], v[138:141], v[174:177], v[44:47]
	v_mfma_f32_16x16x32_bf16 v[40:43], v[150:153], v[174:177], v[40:43]
	v_mfma_f32_16x16x32_bf16 v[28:31], v[138:141], v[182:185], v[28:31]
	v_mfma_f32_16x16x32_bf16 v[24:27], v[150:153], v[182:185], v[24:27]
	v_mfma_f32_16x16x32_bf16 v[12:15], v[138:141], v[208:211], v[12:15]
	v_mfma_f32_16x16x32_bf16 v[8:11], v[150:153], v[208:211], v[8:11]
	v_mfma_f32_16x16x32_bf16 v[60:63], v[142:145], v[170:173], v[60:63]
	v_mfma_f32_16x16x32_bf16 v[56:59], v[154:157], v[170:173], v[56:59]
	v_mfma_f32_16x16x32_bf16 v[44:47], v[142:145], v[178:181], v[44:47]
	v_mfma_f32_16x16x32_bf16 v[40:43], v[154:157], v[178:181], v[40:43]
	v_mfma_f32_16x16x32_bf16 v[28:31], v[142:145], v[196:199], v[28:31]
	v_mfma_f32_16x16x32_bf16 v[24:27], v[154:157], v[196:199], v[24:27]
	v_mfma_f32_16x16x32_bf16 v[12:15], v[142:145], v[212:215], v[12:15]
	v_mfma_f32_16x16x32_bf16 v[8:11], v[154:157], v[212:215], v[8:11]
	s_setprio 0
	s_barrier
	s_add_u32 s36, s36, 0x80080
	s_addc_u32 s37, s37, 0
	s_mov_b32 m0, s61
	v_lshl_add_u64 v[138:139], s[36:37], 0, v[160:161]
	global_load_lds_dwordx4 v[138:139], off
	v_lshl_add_u64 v[138:139], s[36:37], 0, v[132:133]
	s_mov_b32 m0, s62
	s_nop 0
	global_load_lds_dwordx4 v[138:139], off
	s_waitcnt vmcnt(6)
	s_barrier
	s_setprio 1
	v_mfma_f32_16x16x32_bf16 v[52:55], v[216:219], v[166:169], v[52:55]
	v_mfma_f32_16x16x32_bf16 v[48:51], v[224:227], v[166:169], v[48:51]
	v_mfma_f32_16x16x32_bf16 v[36:39], v[216:219], v[174:177], v[36:39]
	v_mfma_f32_16x16x32_bf16 v[32:35], v[224:227], v[174:177], v[32:35]
	v_mfma_f32_16x16x32_bf16 v[20:23], v[216:219], v[182:185], v[20:23]
	v_mfma_f32_16x16x32_bf16 v[16:19], v[224:227], v[182:185], v[16:19]
	v_mfma_f32_16x16x32_bf16 v[4:7], v[216:219], v[208:211], v[4:7]
	v_mfma_f32_16x16x32_bf16 v[0:3], v[224:227], v[208:211], v[0:3]
	v_mfma_f32_16x16x32_bf16 v[52:55], v[220:223], v[170:173], v[52:55]
	v_mfma_f32_16x16x32_bf16 v[48:51], v[228:231], v[170:173], v[48:51]
	v_mfma_f32_16x16x32_bf16 v[36:39], v[220:223], v[178:181], v[36:39]
	v_mfma_f32_16x16x32_bf16 v[32:35], v[228:231], v[178:181], v[32:35]
	v_mfma_f32_16x16x32_bf16 v[20:23], v[220:223], v[196:199], v[20:23]
	v_mfma_f32_16x16x32_bf16 v[16:19], v[228:231], v[196:199], v[16:19]
	v_mfma_f32_16x16x32_bf16 v[4:7], v[220:223], v[212:215], v[4:7]
	v_mfma_f32_16x16x32_bf16 v[0:3], v[228:231], v[212:215], v[0:3]
	s_setprio 0
	s_add_i32 s64, s64, 2
	s_add_u32 s34, s34, 0x100
	s_addc_u32 s35, s35, 0
	s_add_u32 s22, s22, 0x100
	s_addc_u32 s23, s23, 0
	s_cmp_gt_u32 s64, 29
	s_barrier
	s_cbranch_scc0 .LBB0_925
	v_lshl_add_u32 v142, s30, 8, v146
	v_ashrrev_i32_e32 v143, 31, v142
	v_lshl_add_u64 v[138:139], v[142:143], 3, s[10:11]
	v_lshl_or_b32 v140, s0, 8, v148
	v_ashrrev_i32_e32 v141, 31, v140
	s_mov_b64 s[0:1], 0x200000
	s_mov_b32 s30, s18
	s_mov_b64 s[36:37], s[28:29]
	s_mov_b64 s[34:35], s[26:27]
	v_mov_b64_e32 v[144:145], v[236:237]
	v_cvt_f64_u32_e32 v[150:151], v145
	v_ldexp_f64 v[150:151], v[150:151], 32
	v_cvt_f64_u32_e32 v[144:145], v144
	v_add_f64 v[144:145], v[150:151], v[144:145]
	v_ldexp_f64 v[144:145], v[144:145], s93
	v_cvt_f32_f64_e32 v144, v[144:145]
	v_fmamk_f32 v144, v144, 0x3a000000, v189
	v_cmp_gt_f32_e32 vcc, s78, v144
	v_mul_f32_e32 v145, 0x4b800000, v144
	s_nop 0
	v_cndmask_b32_e32 v144, v144, v145, vcc
	v_rsq_f32_e32 v144, v144
	s_nop 0
	v_mul_f32_e32 v145, 0x45800000, v144
	v_cndmask_b32_e32 v150, v144, v145, vcc
	v_pk_mul_f32 v[120:121], v[120:121], v[150:151] op_sel_hi:[1,0]
	v_pk_mul_f32 v[124:125], v[124:125], v[150:151] op_sel_hi:[1,0]
	v_pk_mul_f32 v[122:123], v[122:123], v[150:151] op_sel_hi:[1,0]
	v_max_f32_e32 v120, 0, v120
	v_lshlrev_b64 v[144:145], 14, v[142:143]
	v_pk_mul_f32 v[126:127], v[126:127], v[150:151] op_sel_hi:[1,0]
	v_mul_f32_e32 v143, v120, v120
	v_max_f32_e32 v120, 0, v125
	v_max_f32_e32 v121, 0, v121
	v_max_f32_e32 v122, 0, v122
	v_lshl_add_u64 v[152:153], s[14:15], 0, v[144:145]
	v_lshlrev_b64 v[144:145], 1, v[140:141]
	v_max_f32_e32 v124, 0, v124
	v_mul_f32_e32 v120, v120, v120
	v_mul_f32_e32 v125, v121, v121
	v_max_f32_e32 v121, 0, v126
	v_mul_f32_e32 v126, v122, v122
	v_max_f32_e32 v122, 0, v127
	v_max_f32_e32 v123, 0, v123
	v_pk_mul_f32 v[114:115], v[114:115], v[150:151] op_sel_hi:[1,0]
	v_pk_mul_f32 v[112:113], v[112:113], v[150:151] op_sel_hi:[1,0]
	v_lshl_add_u64 v[140:141], v[152:153], 0, v[144:145]
	v_mul_f32_e32 v124, v124, v124
	v_mul_f32_e32 v121, v121, v121
	v_mul_f32_e32 v122, v122, v122
	v_mul_f32_e32 v123, v123, v123
	v_cvt_pk_bf16_f32 v120, v124, v120
	v_pk_mul_f32 v[118:119], v[118:119], v[150:151] op_sel_hi:[1,0]
	v_pk_mul_f32 v[116:117], v[116:117], v[150:151] op_sel_hi:[1,0]
	v_max_f32_e32 v112, 0, v112
	v_max_f32_e32 v113, 0, v113
	v_max_f32_e32 v114, 0, v114
	v_cvt_pk_bf16_f32 v121, v121, v122
	v_cvt_pk_bf16_f32 v122, v143, v125
	v_cvt_pk_bf16_f32 v123, v126, v123
	global_store_dwordx4 v[140:141], v[120:123], off
	v_max_f32_e32 v115, 0, v115
	v_max_f32_e32 v116, 0, v116
	v_mul_f32_e32 v120, v112, v112
	v_max_f32_e32 v112, 0, v117
	v_mul_f32_e32 v117, v113, v113
	v_max_f32_e32 v113, 0, v118
	v_mul_f32_e32 v118, v114, v114
	v_max_f32_e32 v114, 0, v119
	v_mul_f32_e32 v112, v112, v112
	v_mul_f32_e32 v113, v113, v113
	v_mul_f32_e32 v114, v114, v114
	v_mul_f32_e32 v115, v115, v115
	v_mul_f32_e32 v116, v116, v116
	v_cvt_pk_bf16_f32 v112, v116, v112
	v_cvt_pk_bf16_f32 v113, v113, v114
	v_cvt_pk_bf16_f32 v114, v120, v117
; __device__ __forceinline__ unsigned cvt_pk_bf16(float lo, float hi) { unsigned r; asm volatile("v_cvt_pk_bf16_f32 %0, %1, %2" : "=v"(r) : "v"(lo), "v"(hi)); return r; }
; __device__ __forceinline__ float rinv_st(stat_t s, float invn) { return rsqrtf((float)((double)s * (1.0 / 4294967296.0)) * invn + 1e-6f); }
;     __device__ __forceinline__ void operator()(const f32x4 (&acc)[2][2][4][2], const Unit& u, int wr, int wc, int fr, int fq) const {
;     ...
;                 const int row = row0 + ai * HALF + m * 16; const float r = rinv_st(stats[row], 1.0f / 2048.0f);
;                 bf16_t* rowp = U + (size_t)row * FF + col0;
; #pragma unroll
;                 for (int bj = 0; bj < 2; ++bj) {
;                     f32x4 v0 = acc[ai][bj][m][0] * r, v1 = acc[ai][bj][m][1] * r;
; #pragma unroll
;                     for (int j = 0; j < 4; ++j) { const float a = fmaxf(v0[j], 0.f), b = fmaxf(v1[j], 0.f); v0[j] = a * a; v1[j] = b * b; }
;                     u32x4 w; w.x = cvt_pk_bf16(v0[0], v0[1]); w.y = cvt_pk_bf16(v0[2], v0[3]); w.z = cvt_pk_bf16(v1[0], v1[1]); w.w = cvt_pk_bf16(v1[2], v1[3]);
;                     *(u32x4*)(rowp + bj * HALF) = w;
	v_cvt_pk_bf16_f32 v115, v118, v115
	global_store_dwordx4 v[140:141], v[112:115], off offset:256
	s_nop 1
	v_mov_b64_e32 v[114:115], v[238:239]
	v_cvt_f64_u32_e32 v[116:117], v115
	v_ldexp_f64 v[116:117], v[116:117], 32
	v_cvt_f64_u32_e32 v[114:115], v114
	v_add_f64 v[114:115], v[116:117], v[114:115]
	v_ldexp_f64 v[114:115], v[114:115], s93
	v_cvt_f32_f64_e32 v114, v[114:115]
	v_fmamk_f32 v114, v114, 0x3a000000, v189
	v_cmp_gt_f32_e32 vcc, s78, v114
	v_mul_f32_e32 v115, 0x4b800000, v114
	v_or_b32_e32 v112, 16, v142
	v_cndmask_b32_e32 v114, v114, v115, vcc
	v_rsq_f32_e32 v114, v114
	v_ashrrev_i32_e32 v113, 31, v112
	v_lshlrev_b64 v[112:113], 14, v[112:113]
	v_lshl_add_u64 v[112:113], s[14:15], 0, v[112:113]
	v_mul_f32_e32 v115, 0x45800000, v114
	v_cndmask_b32_e32 v114, v114, v115, vcc
	v_pk_mul_f32 v[104:105], v[104:105], v[114:115] op_sel_hi:[1,0]
	v_pk_mul_f32 v[108:109], v[108:109], v[114:115] op_sel_hi:[1,0]
	v_pk_mul_f32 v[106:107], v[106:107], v[114:115] op_sel_hi:[1,0]
	v_max_f32_e32 v104, 0, v104
	v_pk_mul_f32 v[110:111], v[110:111], v[114:115] op_sel_hi:[1,0]
	v_mul_f32_e32 v115, v104, v104
	v_max_f32_e32 v104, 0, v109
	v_max_f32_e32 v105, 0, v105
	v_max_f32_e32 v106, 0, v106
	v_max_f32_e32 v108, 0, v108
	v_mul_f32_e32 v104, v104, v104
	v_mul_f32_e32 v109, v105, v105
	v_max_f32_e32 v105, 0, v110
	v_mul_f32_e32 v110, v106, v106
	v_max_f32_e32 v106, 0, v111
	v_max_f32_e32 v107, 0, v107
	v_pk_mul_f32 v[98:99], v[98:99], v[114:115] op_sel_hi:[1,0]
	v_pk_mul_f32 v[96:97], v[96:97], v[114:115] op_sel_hi:[1,0]
	v_lshl_add_u64 v[112:113], v[112:113], 0, v[144:145]
	v_mul_f32_e32 v108, v108, v108
	v_mul_f32_e32 v105, v105, v105
	v_mul_f32_e32 v106, v106, v106
	v_mul_f32_e32 v107, v107, v107
	v_cvt_pk_bf16_f32 v104, v108, v104
	v_pk_mul_f32 v[102:103], v[102:103], v[114:115] op_sel_hi:[1,0]
	v_pk_mul_f32 v[100:101], v[100:101], v[114:115] op_sel_hi:[1,0]
	v_max_f32_e32 v96, 0, v96
	v_max_f32_e32 v97, 0, v97
	v_max_f32_e32 v98, 0, v98
	v_cvt_pk_bf16_f32 v105, v105, v106
	v_cvt_pk_bf16_f32 v106, v115, v109
	v_cvt_pk_bf16_f32 v107, v110, v107
	global_store_dwordx4 v[112:113], v[104:107], off
	v_max_f32_e32 v99, 0, v99
	v_max_f32_e32 v100, 0, v100
	v_mul_f32_e32 v104, v96, v96
	v_max_f32_e32 v96, 0, v101
	v_mul_f32_e32 v101, v97, v97
	v_max_f32_e32 v97, 0, v102
	v_mul_f32_e32 v102, v98, v98
	v_max_f32_e32 v98, 0, v103
	v_mul_f32_e32 v96, v96, v96
	v_mul_f32_e32 v97, v97, v97
	v_mul_f32_e32 v98, v98, v98
	v_mul_f32_e32 v99, v99, v99
	v_mul_f32_e32 v100, v100, v100
	v_cvt_pk_bf16_f32 v96, v100, v96
	v_cvt_pk_bf16_f32 v97, v97, v98
	v_cvt_pk_bf16_f32 v98, v104, v101
	v_cvt_pk_bf16_f32 v99, v102, v99
	global_store_dwordx4 v[112:113], v[96:99], off offset:256
	s_nop 1
	v_mov_b64_e32 v[98:99], v[240:241]
	v_cvt_f64_u32_e32 v[100:101], v99
	v_ldexp_f64 v[100:101], v[100:101], 32
	v_cvt_f64_u32_e32 v[98:99], v98
	v_add_f64 v[98:99], v[100:101], v[98:99]
	v_ldexp_f64 v[98:99], v[98:99], s93
	v_cvt_f32_f64_e32 v98, v[98:99]
	v_fmamk_f32 v98, v98, 0x3a000000, v189
	v_cmp_gt_f32_e32 vcc, s78, v98
	v_mul_f32_e32 v99, 0x4b800000, v98
	v_or_b32_e32 v96, 32, v142
	v_cndmask_b32_e32 v98, v98, v99, vcc
	v_rsq_f32_e32 v98, v98
	v_ashrrev_i32_e32 v97, 31, v96
	v_lshlrev_b64 v[96:97], 14, v[96:97]
	v_lshl_add_u64 v[96:97], s[14:15], 0, v[96:97]
	v_mul_f32_e32 v99, 0x45800000, v98
	v_cndmask_b32_e32 v98, v98, v99, vcc
	v_pk_mul_f32 v[88:89], v[88:89], v[98:99] op_sel_hi:[1,0]
	v_pk_mul_f32 v[92:93], v[92:93], v[98:99] op_sel_hi:[1,0]
	v_pk_mul_f32 v[90:91], v[90:91], v[98:99] op_sel_hi:[1,0]
	v_max_f32_e32 v88, 0, v88
	v_pk_mul_f32 v[94:95], v[94:95], v[98:99] op_sel_hi:[1,0]
	v_mul_f32_e32 v99, v88, v88
	v_max_f32_e32 v88, 0, v93
	v_max_f32_e32 v89, 0, v89
	v_max_f32_e32 v90, 0, v90
	v_max_f32_e32 v92, 0, v92
	v_mul_f32_e32 v88, v88, v88
	v_mul_f32_e32 v93, v89, v89
	v_max_f32_e32 v89, 0, v94
	v_mul_f32_e32 v94, v90, v90
	v_max_f32_e32 v90, 0, v95
	v_max_f32_e32 v91, 0, v91
	v_pk_mul_f32 v[82:83], v[82:83], v[98:99] op_sel_hi:[1,0]
	v_pk_mul_f32 v[80:81], v[80:81], v[98:99] op_sel_hi:[1,0]
	v_lshl_add_u64 v[96:97], v[96:97], 0, v[144:145]
	v_mul_f32_e32 v92, v92, v92
	v_mul_f32_e32 v89, v89, v89
	v_mul_f32_e32 v90, v90, v90
	v_mul_f32_e32 v91, v91, v91
	v_cvt_pk_bf16_f32 v88, v92, v88
	v_pk_mul_f32 v[86:87], v[86:87], v[98:99] op_sel_hi:[1,0]
	v_pk_mul_f32 v[84:85], v[84:85], v[98:99] op_sel_hi:[1,0]
	v_max_f32_e32 v80, 0, v80
	v_max_f32_e32 v81, 0, v81
	v_max_f32_e32 v82, 0, v82
	v_cvt_pk_bf16_f32 v89, v89, v90
	v_cvt_pk_bf16_f32 v90, v99, v93
	v_cvt_pk_bf16_f32 v91, v94, v91
	global_store_dwordx4 v[96:97], v[88:91], off
	v_max_f32_e32 v83, 0, v83
	v_max_f32_e32 v84, 0, v84
	v_mul_f32_e32 v88, v80, v80
	v_max_f32_e32 v80, 0, v85
	v_mul_f32_e32 v85, v81, v81
	v_max_f32_e32 v81, 0, v86
	v_mul_f32_e32 v86, v82, v82
	v_max_f32_e32 v82, 0, v87
	v_mul_f32_e32 v80, v80, v80
	v_mul_f32_e32 v81, v81, v81
	v_mul_f32_e32 v82, v82, v82
	v_mul_f32_e32 v83, v83, v83
	v_mul_f32_e32 v84, v84, v84
	v_cvt_pk_bf16_f32 v80, v84, v80
	v_cvt_pk_bf16_f32 v81, v81, v82
	v_cvt_pk_bf16_f32 v82, v88, v85
	v_cvt_pk_bf16_f32 v83, v86, v83
	global_store_dwordx4 v[96:97], v[80:83], off offset:256
	s_nop 1
	v_mov_b64_e32 v[82:83], v[242:243]
	v_cvt_f64_u32_e32 v[84:85], v83
	v_ldexp_f64 v[84:85], v[84:85], 32
	v_cvt_f64_u32_e32 v[82:83], v82
	v_add_f64 v[82:83], v[84:85], v[82:83]
	v_ldexp_f64 v[82:83], v[82:83], s93
	v_cvt_f32_f64_e32 v82, v[82:83]
	v_fmamk_f32 v82, v82, 0x3a000000, v189
	v_cmp_gt_f32_e32 vcc, s78, v82
	v_mul_f32_e32 v83, 0x4b800000, v82
	v_or_b32_e32 v80, 48, v142
	v_cndmask_b32_e32 v82, v82, v83, vcc
	v_rsq_f32_e32 v82, v82
	v_ashrrev_i32_e32 v81, 31, v80
; __device__ __forceinline__ unsigned cvt_pk_bf16(float lo, float hi) { unsigned r; asm volatile("v_cvt_pk_bf16_f32 %0, %1, %2" : "=v"(r) : "v"(lo), "v"(hi)); return r; }
; __device__ __forceinline__ float rinv_st(stat_t s, float invn) { return rsqrtf((float)((double)s * (1.0 / 4294967296.0)) * invn + 1e-6f); }
;     __device__ __forceinline__ void operator()(const f32x4 (&acc)[2][2][4][2], const Unit& u, int wr, int wc, int fr, int fq) const {
;     ...
;                 const int row = row0 + ai * HALF + m * 16; const float r = rinv_st(stats[row], 1.0f / 2048.0f);
;                 bf16_t* rowp = U + (size_t)row * FF + col0;
; #pragma unroll
;                 for (int bj = 0; bj < 2; ++bj) {
;                     f32x4 v0 = acc[ai][bj][m][0] * r, v1 = acc[ai][bj][m][1] * r;
; #pragma unroll
;                     for (int j = 0; j < 4; ++j) { const float a = fmaxf(v0[j], 0.f), b = fmaxf(v1[j], 0.f); v0[j] = a * a; v1[j] = b * b; }
;                     u32x4 w; w.x = cvt_pk_bf16(v0[0], v0[1]); w.y = cvt_pk_bf16(v0[2], v0[3]); w.z = cvt_pk_bf16(v1[0], v1[1]); w.w = cvt_pk_bf16(v1[2], v1[3]);
;                     *(u32x4*)(rowp + bj * HALF) = w;
	v_lshlrev_b64 v[80:81], 14, v[80:81]
	v_lshl_add_u64 v[80:81], s[14:15], 0, v[80:81]
	v_mul_f32_e32 v83, 0x45800000, v82
	v_cndmask_b32_e32 v82, v82, v83, vcc
	v_pk_mul_f32 v[72:73], v[72:73], v[82:83] op_sel_hi:[1,0]
	v_pk_mul_f32 v[76:77], v[76:77], v[82:83] op_sel_hi:[1,0]
	v_pk_mul_f32 v[74:75], v[74:75], v[82:83] op_sel_hi:[1,0]
	v_max_f32_e32 v72, 0, v72
	v_pk_mul_f32 v[78:79], v[78:79], v[82:83] op_sel_hi:[1,0]
	v_mul_f32_e32 v83, v72, v72
	v_max_f32_e32 v72, 0, v77
	v_max_f32_e32 v73, 0, v73
	v_max_f32_e32 v74, 0, v74
	v_max_f32_e32 v76, 0, v76
	v_mul_f32_e32 v72, v72, v72
	v_mul_f32_e32 v77, v73, v73
	v_max_f32_e32 v73, 0, v78
	v_mul_f32_e32 v78, v74, v74
	v_max_f32_e32 v74, 0, v79
	v_max_f32_e32 v75, 0, v75
	v_pk_mul_f32 v[66:67], v[66:67], v[82:83] op_sel_hi:[1,0]
	v_pk_mul_f32 v[64:65], v[64:65], v[82:83] op_sel_hi:[1,0]
	v_lshl_add_u64 v[80:81], v[80:81], 0, v[144:145]
	v_mul_f32_e32 v76, v76, v76
	v_mul_f32_e32 v73, v73, v73
	v_mul_f32_e32 v74, v74, v74
	v_mul_f32_e32 v75, v75, v75
	v_cvt_pk_bf16_f32 v72, v76, v72
	v_pk_mul_f32 v[70:71], v[70:71], v[82:83] op_sel_hi:[1,0]
	v_pk_mul_f32 v[68:69], v[68:69], v[82:83] op_sel_hi:[1,0]
	v_max_f32_e32 v64, 0, v64
	v_max_f32_e32 v65, 0, v65
	v_max_f32_e32 v66, 0, v66
	v_cvt_pk_bf16_f32 v73, v73, v74
	v_cvt_pk_bf16_f32 v74, v83, v77
	v_cvt_pk_bf16_f32 v75, v78, v75
	global_store_dwordx4 v[80:81], v[72:75], off
	v_max_f32_e32 v67, 0, v67
	v_max_f32_e32 v68, 0, v68
	v_mul_f32_e32 v72, v64, v64
	v_max_f32_e32 v64, 0, v69
	v_mul_f32_e32 v69, v65, v65
	v_max_f32_e32 v65, 0, v70
	v_mul_f32_e32 v70, v66, v66
	v_max_f32_e32 v66, 0, v71
	v_mul_f32_e32 v64, v64, v64
	v_mul_f32_e32 v65, v65, v65
	v_mul_f32_e32 v66, v66, v66
	v_mul_f32_e32 v67, v67, v67
	v_mul_f32_e32 v68, v68, v68
	v_cvt_pk_bf16_f32 v64, v68, v64
	v_cvt_pk_bf16_f32 v65, v65, v66
	v_cvt_pk_bf16_f32 v66, v72, v69
	v_cvt_pk_bf16_f32 v67, v70, v67
	global_store_dwordx4 v[80:81], v[64:67], off offset:256
	s_nop 1
	v_mov_b64_e32 v[64:65], v[244:245]
	v_cvt_f64_u32_e32 v[66:67], v65
	v_ldexp_f64 v[66:67], v[66:67], 32
	v_cvt_f64_u32_e32 v[64:65], v64
	v_add_f64 v[64:65], v[66:67], v[64:65]
	v_ldexp_f64 v[64:65], v[64:65], s93
	v_cvt_f32_f64_e32 v64, v[64:65]
	v_fmamk_f32 v64, v64, 0x3a000000, v189
	v_cmp_gt_f32_e32 vcc, s78, v64
	v_mul_f32_e32 v65, 0x4b800000, v64
	s_nop 0
	v_cndmask_b32_e32 v64, v64, v65, vcc
	v_rsq_f32_e32 v64, v64
	s_nop 0
	v_mul_f32_e32 v65, 0x45800000, v64
	v_cndmask_b32_e32 v66, v64, v65, vcc
	v_pk_mul_f32 v[56:57], v[56:57], v[66:67] op_sel_hi:[1,0]
	v_pk_mul_f32 v[60:61], v[60:61], v[66:67] op_sel_hi:[1,0]
	v_pk_mul_f32 v[58:59], v[58:59], v[66:67] op_sel_hi:[1,0]
	v_max_f32_e32 v56, 0, v56
	v_pk_mul_f32 v[62:63], v[62:63], v[66:67] op_sel_hi:[1,0]
	v_max_f32_e32 v60, 0, v60
	v_mul_f32_e32 v67, v56, v56
	v_max_f32_e32 v56, 0, v61
	v_max_f32_e32 v57, 0, v57
	v_max_f32_e32 v58, 0, v58
	v_lshl_add_u64 v[64:65], v[140:141], 0, s[0:1]
	v_mul_f32_e32 v60, v60, v60
	v_mul_f32_e32 v56, v56, v56
	v_mul_f32_e32 v61, v57, v57
	v_max_f32_e32 v57, 0, v62
	v_mul_f32_e32 v62, v58, v58
	v_max_f32_e32 v58, 0, v63
	s_mov_b32 s0, 0x200000
	v_mul_f32_e32 v57, v57, v57
	v_max_f32_e32 v59, 0, v59
	v_mul_f32_e32 v58, v58, v58
	v_cvt_pk_bf16_f32 v56, v60, v56
	v_add_co_u32_e32 v60, vcc, s0, v140
	v_pk_mul_f32 v[50:51], v[50:51], v[66:67] op_sel_hi:[1,0]
	v_pk_mul_f32 v[48:49], v[48:49], v[66:67] op_sel_hi:[1,0]
	v_mul_f32_e32 v59, v59, v59
	v_cvt_pk_bf16_f32 v57, v57, v58
	v_cvt_pk_bf16_f32 v58, v67, v61
	v_addc_co_u32_e32 v61, vcc, 0, v141, vcc
	v_pk_mul_f32 v[54:55], v[54:55], v[66:67] op_sel_hi:[1,0]
	v_pk_mul_f32 v[52:53], v[52:53], v[66:67] op_sel_hi:[1,0]
	v_max_f32_e32 v48, 0, v48
	v_max_f32_e32 v49, 0, v49
	v_max_f32_e32 v50, 0, v50
	v_cvt_pk_bf16_f32 v59, v62, v59
	global_store_dwordx4 v[60:61], v[56:59], off
	v_max_f32_e32 v51, 0, v51
	v_max_f32_e32 v52, 0, v52
	v_mul_f32_e32 v56, v48, v48
	v_max_f32_e32 v48, 0, v53
	v_mul_f32_e32 v53, v49, v49
	v_max_f32_e32 v49, 0, v54
	v_mul_f32_e32 v54, v50, v50
	v_max_f32_e32 v50, 0, v55
	v_mul_f32_e32 v48, v48, v48
	v_mul_f32_e32 v49, v49, v49
	v_mul_f32_e32 v50, v50, v50
	v_mul_f32_e32 v51, v51, v51
	v_mul_f32_e32 v52, v52, v52
	v_cvt_pk_bf16_f32 v48, v52, v48
	v_cvt_pk_bf16_f32 v49, v49, v50
	v_cvt_pk_bf16_f32 v50, v56, v53
	v_cvt_pk_bf16_f32 v51, v54, v51
	global_store_dwordx4 v[64:65], v[48:51], off offset:256
	s_nop 1
	v_mov_b64_e32 v[48:49], v[246:247]
	s_mov_b64 s[0:1], 0x240000
	v_cvt_f64_u32_e32 v[50:51], v49
	v_ldexp_f64 v[50:51], v[50:51], 32
	v_cvt_f64_u32_e32 v[48:49], v48
	v_add_f64 v[48:49], v[50:51], v[48:49]
	v_ldexp_f64 v[48:49], v[48:49], s93
	v_cvt_f32_f64_e32 v48, v[48:49]
	v_fmamk_f32 v48, v48, 0x3a000000, v189
	v_cmp_gt_f32_e32 vcc, s78, v48
	v_mul_f32_e32 v49, 0x4b800000, v48
	s_nop 0
	v_cndmask_b32_e32 v48, v48, v49, vcc
	v_rsq_f32_e32 v48, v48
	s_nop 0
	v_mul_f32_e32 v49, 0x45800000, v48
	v_cndmask_b32_e32 v50, v48, v49, vcc
	v_pk_mul_f32 v[40:41], v[40:41], v[50:51] op_sel_hi:[1,0]
	v_pk_mul_f32 v[44:45], v[44:45], v[50:51] op_sel_hi:[1,0]
	v_pk_mul_f32 v[42:43], v[42:43], v[50:51] op_sel_hi:[1,0]
	v_max_f32_e32 v40, 0, v40
	v_pk_mul_f32 v[46:47], v[46:47], v[50:51] op_sel_hi:[1,0]
	v_max_f32_e32 v44, 0, v44
	v_mul_f32_e32 v51, v40, v40
	v_max_f32_e32 v40, 0, v45
	v_max_f32_e32 v41, 0, v41
	v_max_f32_e32 v42, 0, v42
	v_lshl_add_u64 v[48:49], v[140:141], 0, s[0:1]
	v_mul_f32_e32 v44, v44, v44
	v_mul_f32_e32 v40, v40, v40
	v_mul_f32_e32 v45, v41, v41
	v_max_f32_e32 v41, 0, v46
	v_mul_f32_e32 v46, v42, v42
	v_max_f32_e32 v42, 0, v47
	s_mov_b32 s0, 0x240000
	v_mul_f32_e32 v41, v41, v41
	v_max_f32_e32 v43, 0, v43
	v_mul_f32_e32 v42, v42, v42
; __device__ __forceinline__ unsigned cvt_pk_bf16(float lo, float hi) { unsigned r; asm volatile("v_cvt_pk_bf16_f32 %0, %1, %2" : "=v"(r) : "v"(lo), "v"(hi)); return r; }
; __device__ __forceinline__ float rinv_st(stat_t s, float invn) { return rsqrtf((float)((double)s * (1.0 / 4294967296.0)) * invn + 1e-6f); }
;     __device__ __forceinline__ void operator()(const f32x4 (&acc)[2][2][4][2], const Unit& u, int wr, int wc, int fr, int fq) const {
;     ...
;                 const int row = row0 + ai * HALF + m * 16; const float r = rinv_st(stats[row], 1.0f / 2048.0f);
;                 bf16_t* rowp = U + (size_t)row * FF + col0;
; #pragma unroll
;                 for (int bj = 0; bj < 2; ++bj) {
;                     f32x4 v0 = acc[ai][bj][m][0] * r, v1 = acc[ai][bj][m][1] * r;
; #pragma unroll
;                     for (int j = 0; j < 4; ++j) { const float a = fmaxf(v0[j], 0.f), b = fmaxf(v1[j], 0.f); v0[j] = a * a; v1[j] = b * b; }
;                     u32x4 w; w.x = cvt_pk_bf16(v0[0], v0[1]); w.y = cvt_pk_bf16(v0[2], v0[3]); w.z = cvt_pk_bf16(v1[0], v1[1]); w.w = cvt_pk_bf16(v1[2], v1[3]);
;                     *(u32x4*)(rowp + bj * HALF) = w;
	v_cvt_pk_bf16_f32 v40, v44, v40
	v_add_co_u32_e32 v44, vcc, s0, v140
	v_pk_mul_f32 v[34:35], v[34:35], v[50:51] op_sel_hi:[1,0]
	v_pk_mul_f32 v[32:33], v[32:33], v[50:51] op_sel_hi:[1,0]
	v_mul_f32_e32 v43, v43, v43
	v_cvt_pk_bf16_f32 v41, v41, v42
	v_cvt_pk_bf16_f32 v42, v51, v45
	v_addc_co_u32_e32 v45, vcc, 0, v141, vcc
	v_pk_mul_f32 v[38:39], v[38:39], v[50:51] op_sel_hi:[1,0]
	v_pk_mul_f32 v[36:37], v[36:37], v[50:51] op_sel_hi:[1,0]
	v_max_f32_e32 v32, 0, v32
	v_max_f32_e32 v33, 0, v33
	v_max_f32_e32 v34, 0, v34
	v_cvt_pk_bf16_f32 v43, v46, v43
	global_store_dwordx4 v[44:45], v[40:43], off
	v_max_f32_e32 v35, 0, v35
	v_max_f32_e32 v36, 0, v36
	v_mul_f32_e32 v40, v32, v32
	v_max_f32_e32 v32, 0, v37
	v_mul_f32_e32 v37, v33, v33
	v_max_f32_e32 v33, 0, v38
	v_mul_f32_e32 v38, v34, v34
	v_max_f32_e32 v34, 0, v39
	v_mul_f32_e32 v32, v32, v32
	v_mul_f32_e32 v33, v33, v33
	v_mul_f32_e32 v34, v34, v34
	v_mul_f32_e32 v35, v35, v35
	v_mul_f32_e32 v36, v36, v36
	v_cvt_pk_bf16_f32 v32, v36, v32
	v_cvt_pk_bf16_f32 v33, v33, v34
	v_cvt_pk_bf16_f32 v34, v40, v37
	v_cvt_pk_bf16_f32 v35, v38, v35
	global_store_dwordx4 v[48:49], v[32:35], off offset:256
	s_nop 1
	v_mov_b64_e32 v[32:33], v[248:249]
	s_mov_b64 s[0:1], 0x280000
	v_cvt_f64_u32_e32 v[34:35], v33
	v_ldexp_f64 v[34:35], v[34:35], 32
	v_cvt_f64_u32_e32 v[32:33], v32
	v_add_f64 v[32:33], v[34:35], v[32:33]
	v_ldexp_f64 v[32:33], v[32:33], s93
	v_cvt_f32_f64_e32 v32, v[32:33]
	v_fmamk_f32 v32, v32, 0x3a000000, v189
	v_cmp_gt_f32_e32 vcc, s78, v32
	v_mul_f32_e32 v33, 0x4b800000, v32
	s_nop 0
	v_cndmask_b32_e32 v32, v32, v33, vcc
	v_rsq_f32_e32 v32, v32
	s_nop 0
	v_mul_f32_e32 v33, 0x45800000, v32
	v_cndmask_b32_e32 v34, v32, v33, vcc
	v_pk_mul_f32 v[24:25], v[24:25], v[34:35] op_sel_hi:[1,0]
	v_pk_mul_f32 v[28:29], v[28:29], v[34:35] op_sel_hi:[1,0]
	v_pk_mul_f32 v[26:27], v[26:27], v[34:35] op_sel_hi:[1,0]
	v_max_f32_e32 v24, 0, v24
	v_pk_mul_f32 v[30:31], v[30:31], v[34:35] op_sel_hi:[1,0]
	v_max_f32_e32 v28, 0, v28
	v_mul_f32_e32 v35, v24, v24
	v_max_f32_e32 v24, 0, v29
	v_max_f32_e32 v25, 0, v25
	v_max_f32_e32 v26, 0, v26
	v_lshl_add_u64 v[32:33], v[140:141], 0, s[0:1]
	v_mul_f32_e32 v28, v28, v28
	v_mul_f32_e32 v24, v24, v24
	v_mul_f32_e32 v29, v25, v25
	v_max_f32_e32 v25, 0, v30
	v_mul_f32_e32 v30, v26, v26
	v_max_f32_e32 v26, 0, v31
	s_mov_b32 s0, 0x280000
	v_mul_f32_e32 v25, v25, v25
	v_max_f32_e32 v27, 0, v27
	v_mul_f32_e32 v26, v26, v26
	v_cvt_pk_bf16_f32 v24, v28, v24
	v_add_co_u32_e32 v28, vcc, s0, v140
	v_pk_mul_f32 v[18:19], v[18:19], v[34:35] op_sel_hi:[1,0]
	v_pk_mul_f32 v[16:17], v[16:17], v[34:35] op_sel_hi:[1,0]
	v_mul_f32_e32 v27, v27, v27
	v_cvt_pk_bf16_f32 v25, v25, v26
	v_cvt_pk_bf16_f32 v26, v35, v29
	v_addc_co_u32_e32 v29, vcc, 0, v141, vcc
	v_pk_mul_f32 v[22:23], v[22:23], v[34:35] op_sel_hi:[1,0]
	v_pk_mul_f32 v[20:21], v[20:21], v[34:35] op_sel_hi:[1,0]
	v_max_f32_e32 v16, 0, v16
	v_max_f32_e32 v17, 0, v17
	v_max_f32_e32 v18, 0, v18
	v_cvt_pk_bf16_f32 v27, v30, v27
	global_store_dwordx4 v[28:29], v[24:27], off
	v_max_f32_e32 v19, 0, v19
	v_max_f32_e32 v20, 0, v20
	v_mul_f32_e32 v24, v16, v16
	v_max_f32_e32 v16, 0, v21
	v_mul_f32_e32 v21, v17, v17
	v_max_f32_e32 v17, 0, v22
	v_mul_f32_e32 v22, v18, v18
	v_max_f32_e32 v18, 0, v23
	v_mul_f32_e32 v16, v16, v16
	v_mul_f32_e32 v17, v17, v17
	v_mul_f32_e32 v18, v18, v18
	v_mul_f32_e32 v19, v19, v19
	v_mul_f32_e32 v20, v20, v20
	v_cvt_pk_bf16_f32 v16, v20, v16
	v_cvt_pk_bf16_f32 v17, v17, v18
	v_cvt_pk_bf16_f32 v18, v24, v21
	v_cvt_pk_bf16_f32 v19, v22, v19
	global_store_dwordx4 v[32:33], v[16:19], off offset:256
	s_nop 1
	v_mov_b64_e32 v[16:17], v[250:251]
	s_mov_b64 s[0:1], 0x2c0000
	v_cvt_f64_u32_e32 v[18:19], v17
	v_ldexp_f64 v[18:19], v[18:19], 32
	v_cvt_f64_u32_e32 v[16:17], v16
	v_add_f64 v[16:17], v[18:19], v[16:17]
	v_ldexp_f64 v[16:17], v[16:17], s93
	v_cvt_f32_f64_e32 v16, v[16:17]
	v_fmamk_f32 v16, v16, 0x3a000000, v189
	v_cmp_gt_f32_e32 vcc, s78, v16
	v_mul_f32_e32 v17, 0x4b800000, v16
	v_lshl_add_u64 v[18:19], v[140:141], 0, s[0:1]
	v_cndmask_b32_e32 v16, v16, v17, vcc
	v_rsq_f32_e32 v16, v16
	s_mov_b32 s0, 0x2c0000
	v_mul_f32_e32 v17, 0x45800000, v16
	v_cndmask_b32_e32 v16, v16, v17, vcc
	v_pk_mul_f32 v[8:9], v[8:9], v[16:17] op_sel_hi:[1,0]
	v_pk_mul_f32 v[12:13], v[12:13], v[16:17] op_sel_hi:[1,0]
	v_pk_mul_f32 v[10:11], v[10:11], v[16:17] op_sel_hi:[1,0]
	v_max_f32_e32 v8, 0, v8
	v_pk_mul_f32 v[14:15], v[14:15], v[16:17] op_sel_hi:[1,0]
	v_max_f32_e32 v12, 0, v12
	v_mul_f32_e32 v17, v8, v8
	v_max_f32_e32 v8, 0, v13
	v_max_f32_e32 v9, 0, v9
	v_max_f32_e32 v10, 0, v10
	v_mul_f32_e32 v12, v12, v12
	v_mul_f32_e32 v8, v8, v8
	v_mul_f32_e32 v13, v9, v9
	v_max_f32_e32 v9, 0, v14
	v_mul_f32_e32 v14, v10, v10
	v_max_f32_e32 v10, 0, v15
	v_mul_f32_e32 v9, v9, v9
	v_max_f32_e32 v11, 0, v11
	v_mul_f32_e32 v10, v10, v10
	v_cvt_pk_bf16_f32 v8, v12, v8
	v_add_co_u32_e32 v12, vcc, s0, v140
	v_pk_mul_f32 v[2:3], v[2:3], v[16:17] op_sel_hi:[1,0]
	v_pk_mul_f32 v[0:1], v[0:1], v[16:17] op_sel_hi:[1,0]
	v_mul_f32_e32 v11, v11, v11
	v_cvt_pk_bf16_f32 v9, v9, v10
	v_cvt_pk_bf16_f32 v10, v17, v13
	v_addc_co_u32_e32 v13, vcc, 0, v141, vcc
	v_pk_mul_f32 v[6:7], v[6:7], v[16:17] op_sel_hi:[1,0]
	v_pk_mul_f32 v[4:5], v[4:5], v[16:17] op_sel_hi:[1,0]
	v_max_f32_e32 v0, 0, v0
	v_max_f32_e32 v1, 0, v1
	v_max_f32_e32 v2, 0, v2
	v_cvt_pk_bf16_f32 v11, v14, v11
	global_store_dwordx4 v[12:13], v[8:11], off
	v_max_f32_e32 v3, 0, v3
	v_max_f32_e32 v4, 0, v4
	v_mul_f32_e32 v8, v0, v0
	v_max_f32_e32 v0, 0, v5
	v_mul_f32_e32 v5, v1, v1
	v_max_f32_e32 v1, 0, v6
	v_mul_f32_e32 v6, v2, v2
	v_max_f32_e32 v2, 0, v7
	v_mul_f32_e32 v0, v0, v0
	v_mul_f32_e32 v1, v1, v1
	v_mul_f32_e32 v2, v2, v2
	v_mul_f32_e32 v3, v3, v3
	s_and_b64 vcc, exec, s[8:9]
	s_mov_b32 s0, s16
	v_mul_f32_e32 v4, v4, v4
	v_cvt_pk_bf16_f32 v0, v4, v0
	v_cvt_pk_bf16_f32 v1, v1, v2
	v_cvt_pk_bf16_f32 v2, v8, v5
	v_cvt_pk_bf16_f32 v3, v6, v3
	global_store_dwordx4 v[18:19], v[0:3], off offset:256
	s_cbranch_vccz .LBB0_918
	s_waitcnt vmcnt(0)
	s_cmpk_gt_u32 s42, 0xff
	s_cbranch_scc1 .LBB0_929
	s_barrier
